# E5+E1b+E13: K-loop MFMAs reordered so both k-steps of an accumulator issue back to back
# speedup vs baseline: 1.0160x; 1.0037x over previous
.LBB0_225:
	ds_read_b128 v[128:131], v157
	ds_read_b128 v[132:135], v157 offset:1024
	ds_read_b128 v[146:149], v157 offset:2048
	ds_read_b128 v[164:167], v157 offset:3072
	ds_read_b128 v[168:171], v159
	ds_read_b128 v[172:175], v159 offset:1024
	ds_read_b128 v[176:179], v159 offset:2048
	ds_read_b128 v[180:183], v159 offset:3072
	s_add_u32 s36, s22, 0xfff80080
	s_addc_u32 s37, s23, -1
	s_cmp_eq_u32 s78, 28
	s_cselect_b32 s81, s5, s37
	s_cselect_b32 s80, s14, s36
	s_cselect_b32 vcc_hi, s20, s45
	s_cselect_b32 vcc_lo, s21, s24
	s_add_i32 m0, s77, 0xc000
	ds_read_b128 v[184:187], v161
	ds_read_b128 v[188:191], v161 offset:1024
	ds_read_b128 v[192:195], v161 offset:2048
	ds_read_b128 v[196:199], v161 offset:3072
	ds_read_b128 v[200:203], v161 offset:4096
	ds_read_b128 v[204:207], v161 offset:5120
	ds_read_b128 v[208:211], v161 offset:6144
	ds_read_b128 v[212:215], v161 offset:7168
	global_load_lds_dwordx4 v140, s[22:23]
	s_add_i32 m0, s77, 0xe000
	s_nop 0
	s_add_u32 s98, s22, s6
	s_addc_u32 s99, s23, s7
	global_load_lds_dwordx4 v140, s[98:99]
	s_waitcnt vmcnt(8)
	s_waitcnt lgkmcnt(0)
	s_barrier
	s_setprio 1
	s_waitcnt lgkmcnt(0)
	v_mfma_i32_16x16x64_i8 v[0:3], v[128:131], v[184:187], v[0:3]
	v_mfma_i32_16x16x64_i8 v[0:3], v[132:135], v[188:191], v[0:3]
	v_mfma_i32_16x16x64_i8 v[56:59], v[146:149], v[184:187], v[56:59]
	v_mfma_i32_16x16x64_i8 v[56:59], v[164:167], v[188:191], v[56:59]
	v_mfma_i32_16x16x64_i8 v[4:7], v[128:131], v[192:195], v[4:7]
	v_mfma_i32_16x16x64_i8 v[4:7], v[132:135], v[196:199], v[4:7]
	v_mfma_i32_16x16x64_i8 v[52:55], v[146:149], v[192:195], v[52:55]
	v_mfma_i32_16x16x64_i8 v[52:55], v[164:167], v[196:199], v[52:55]
	v_mfma_i32_16x16x64_i8 v[12:15], v[128:131], v[200:203], v[12:15]
	v_mfma_i32_16x16x64_i8 v[12:15], v[132:135], v[204:207], v[12:15]
	v_mfma_i32_16x16x64_i8 v[48:51], v[146:149], v[200:203], v[48:51]
	v_mfma_i32_16x16x64_i8 v[48:51], v[164:167], v[204:207], v[48:51]
	v_mfma_i32_16x16x64_i8 v[8:11], v[128:131], v[208:211], v[8:11]
	v_mfma_i32_16x16x64_i8 v[8:11], v[132:135], v[212:215], v[8:11]
	v_mfma_i32_16x16x64_i8 v[44:47], v[146:149], v[208:211], v[44:47]
	v_mfma_i32_16x16x64_i8 v[44:47], v[164:167], v[212:215], v[44:47]
	s_setprio 0
	s_setprio 1
	v_mfma_i32_16x16x64_i8 v[88:91], v[168:171], v[184:187], v[88:91]
	v_mfma_i32_16x16x64_i8 v[88:91], v[172:175], v[188:191], v[88:91]
	v_mfma_i32_16x16x64_i8 v[120:123], v[176:179], v[184:187], v[120:123]
	v_mfma_i32_16x16x64_i8 v[120:123], v[180:183], v[188:191], v[120:123]
	v_mfma_i32_16x16x64_i8 v[84:87], v[168:171], v[192:195], v[84:87]
	v_mfma_i32_16x16x64_i8 v[84:87], v[172:175], v[196:199], v[84:87]
	v_mfma_i32_16x16x64_i8 v[116:119], v[176:179], v[192:195], v[116:119]
	v_mfma_i32_16x16x64_i8 v[116:119], v[180:183], v[196:199], v[116:119]
	v_mfma_i32_16x16x64_i8 v[80:83], v[168:171], v[200:203], v[80:83]
	v_mfma_i32_16x16x64_i8 v[80:83], v[172:175], v[204:207], v[80:83]
	v_mfma_i32_16x16x64_i8 v[112:115], v[176:179], v[200:203], v[112:115]
	v_mfma_i32_16x16x64_i8 v[112:115], v[180:183], v[204:207], v[112:115]
	s_setprio 2
	s_barrier
	v_mfma_i32_16x16x64_i8 v[76:79], v[168:171], v[208:211], v[76:79]
	v_mfma_i32_16x16x64_i8 v[76:79], v[172:175], v[212:215], v[76:79]
	v_mfma_i32_16x16x64_i8 v[108:111], v[176:179], v[208:211], v[108:111]
	v_mfma_i32_16x16x64_i8 v[108:111], v[180:183], v[212:215], v[108:111]
	s_setprio 0
	s_add_i32 s36, s86, s63
	s_mov_b32 m0, s36
	ds_read_b128 v[184:187], v161 offset:16384
	ds_read_b128 v[188:191], v161 offset:17408
	ds_read_b128 v[192:195], v161 offset:18432
	ds_read_b128 v[196:199], v161 offset:19456
	ds_read_b128 v[200:203], v161 offset:20480
	ds_read_b128 v[204:207], v161 offset:21504
	ds_read_b128 v[208:211], v161 offset:22528
	ds_read_b128 v[212:215], v161 offset:23552
	global_load_lds_dwordx4 v138, vcc
	s_add_i32 m0, s36, 0x2000
	s_add_i32 s36, s87, s63
	s_add_u32 s98, vcc_lo, s6
	s_addc_u32 s99, vcc_hi, s7
	global_load_lds_dwordx4 v138, s[98:99]
	s_mov_b32 m0, s36
	s_nop 0
	s_add_u32 s98, vcc_lo, s8
	s_addc_u32 s99, vcc_hi, s9
	global_load_lds_dwordx4 v138, s[98:99]
	s_add_i32 m0, s36, 0x2000
	s_nop 0
	s_add_u32 s98, vcc_lo, s10
	s_addc_u32 s99, vcc_hi, s11
	global_load_lds_dwordx4 v138, s[98:99]
	s_mov_b32 m0, s77
	s_nop 0
	global_load_lds_dwordx4 v136, s[80:81]
	s_mov_b32 m0, s97
	s_nop 0
	s_add_u32 s98, s80, s6
	s_addc_u32 s99, s81, s7
	global_load_lds_dwordx4 v136, s[98:99]
	s_waitcnt vmcnt(8)
	s_waitcnt lgkmcnt(0)
	s_barrier
	s_setprio 1
	s_waitcnt lgkmcnt(0)
	v_mfma_i32_16x16x64_i8 v[20:23], v[128:131], v[184:187], v[20:23]
	v_mfma_i32_16x16x64_i8 v[20:23], v[132:135], v[188:191], v[20:23]
	v_mfma_i32_16x16x64_i8 v[40:43], v[146:149], v[184:187], v[40:43]
	v_mfma_i32_16x16x64_i8 v[40:43], v[164:167], v[188:191], v[40:43]
	v_mfma_i32_16x16x64_i8 v[16:19], v[128:131], v[192:195], v[16:19]
	v_mfma_i32_16x16x64_i8 v[16:19], v[132:135], v[196:199], v[16:19]
	v_mfma_i32_16x16x64_i8 v[36:39], v[146:149], v[192:195], v[36:39]
	v_mfma_i32_16x16x64_i8 v[36:39], v[164:167], v[196:199], v[36:39]
	v_mfma_i32_16x16x64_i8 v[24:27], v[128:131], v[200:203], v[24:27]
	v_mfma_i32_16x16x64_i8 v[24:27], v[132:135], v[204:207], v[24:27]
	v_mfma_i32_16x16x64_i8 v[32:35], v[146:149], v[200:203], v[32:35]
	v_mfma_i32_16x16x64_i8 v[32:35], v[164:167], v[204:207], v[32:35]
	v_mfma_i32_16x16x64_i8 v[28:31], v[128:131], v[208:211], v[28:31]
	v_mfma_i32_16x16x64_i8 v[28:31], v[132:135], v[212:215], v[28:31]
	v_mfma_i32_16x16x64_i8 v[60:63], v[146:149], v[208:211], v[60:63]
	v_mfma_i32_16x16x64_i8 v[60:63], v[164:167], v[212:215], v[60:63]
	s_setprio 0
	s_setprio 1
	v_mfma_i32_16x16x64_i8 v[72:75], v[168:171], v[184:187], v[72:75]
	v_mfma_i32_16x16x64_i8 v[72:75], v[172:175], v[188:191], v[72:75]
	v_mfma_i32_16x16x64_i8 v[104:107], v[176:179], v[184:187], v[104:107]
	v_mfma_i32_16x16x64_i8 v[104:107], v[180:183], v[188:191], v[104:107]
	v_mfma_i32_16x16x64_i8 v[68:71], v[168:171], v[192:195], v[68:71]
	v_mfma_i32_16x16x64_i8 v[68:71], v[172:175], v[196:199], v[68:71]
	v_mfma_i32_16x16x64_i8 v[100:103], v[176:179], v[192:195], v[100:103]
	v_mfma_i32_16x16x64_i8 v[100:103], v[180:183], v[196:199], v[100:103]
	v_mfma_i32_16x16x64_i8 v[64:67], v[168:171], v[200:203], v[64:67]
	v_mfma_i32_16x16x64_i8 v[64:67], v[172:175], v[204:207], v[64:67]
	v_mfma_i32_16x16x64_i8 v[96:99], v[176:179], v[200:203], v[96:99]
	v_mfma_i32_16x16x64_i8 v[96:99], v[180:183], v[204:207], v[96:99]
	s_setprio 2
	s_barrier
	v_mfma_i32_16x16x64_i8 v[92:95], v[168:171], v[208:211], v[92:95]
	v_mfma_i32_16x16x64_i8 v[92:95], v[172:175], v[212:215], v[92:95]
	v_mfma_i32_16x16x64_i8 v[124:127], v[176:179], v[208:211], v[124:127]
	v_mfma_i32_16x16x64_i8 v[124:127], v[180:183], v[212:215], v[124:127]
	s_setprio 0
	s_add_i32 s36, 0, 0x18000
	v_add_u32_e32 v152, s36, v153
	s_add_i32 s37, 0, 0x1c000
	ds_read_b128 v[128:131], v152
	ds_read_b128 v[132:135], v152 offset:1024
	ds_read_b128 v[146:149], v152 offset:2048
	ds_read_b128 v[164:167], v152 offset:3072
	v_add_u32_e32 v152, s37, v153
	ds_read_b128 v[168:171], v152
	ds_read_b128 v[172:175], v152 offset:1024
	ds_read_b128 v[176:179], v152 offset:2048
	ds_read_b128 v[180:183], v152 offset:3072
	s_mov_b32 m0, s33
	ds_read_b128 v[184:187], v161 offset:32768
	ds_read_b128 v[188:191], v161 offset:33792
	ds_read_b128 v[192:195], v161 offset:34816
	ds_read_b128 v[196:199], v161 offset:35840
	ds_read_b128 v[200:203], v161 offset:36864
	ds_read_b128 v[204:207], v161 offset:37888
	ds_read_b128 v[208:211], v161 offset:38912
	ds_read_b128 v[212:215], v161 offset:39936
	s_add_u32 s98, s80, s8
	s_addc_u32 s99, s81, s9
	global_load_lds_dwordx4 v136, s[98:99]
	s_mov_b32 m0, s93
	s_nop 0
	s_add_u32 s98, s80, s10
	s_addc_u32 s99, s81, s11
	global_load_lds_dwordx4 v136, s[98:99]
	s_waitcnt vmcnt(8)
	s_waitcnt lgkmcnt(0)
	s_barrier
	s_setprio 1
	s_waitcnt lgkmcnt(0)
	v_mfma_i32_16x16x64_i8 v[0:3], v[128:131], v[184:187], v[0:3]
	v_mfma_i32_16x16x64_i8 v[0:3], v[132:135], v[188:191], v[0:3]
	v_mfma_i32_16x16x64_i8 v[56:59], v[146:149], v[184:187], v[56:59]
	v_mfma_i32_16x16x64_i8 v[56:59], v[164:167], v[188:191], v[56:59]
	v_mfma_i32_16x16x64_i8 v[4:7], v[128:131], v[192:195], v[4:7]
	v_mfma_i32_16x16x64_i8 v[4:7], v[132:135], v[196:199], v[4:7]
	v_mfma_i32_16x16x64_i8 v[52:55], v[146:149], v[192:195], v[52:55]
	v_mfma_i32_16x16x64_i8 v[52:55], v[164:167], v[196:199], v[52:55]
	v_mfma_i32_16x16x64_i8 v[12:15], v[128:131], v[200:203], v[12:15]
	v_mfma_i32_16x16x64_i8 v[12:15], v[132:135], v[204:207], v[12:15]
	v_mfma_i32_16x16x64_i8 v[48:51], v[146:149], v[200:203], v[48:51]
	v_mfma_i32_16x16x64_i8 v[48:51], v[164:167], v[204:207], v[48:51]
	v_mfma_i32_16x16x64_i8 v[8:11], v[128:131], v[208:211], v[8:11]
	v_mfma_i32_16x16x64_i8 v[8:11], v[132:135], v[212:215], v[8:11]
	v_mfma_i32_16x16x64_i8 v[44:47], v[146:149], v[208:211], v[44:47]
	v_mfma_i32_16x16x64_i8 v[44:47], v[164:167], v[212:215], v[44:47]
	s_setprio 0
	s_setprio 1
	v_mfma_i32_16x16x64_i8 v[88:91], v[168:171], v[184:187], v[88:91]
	v_mfma_i32_16x16x64_i8 v[88:91], v[172:175], v[188:191], v[88:91]
	v_mfma_i32_16x16x64_i8 v[120:123], v[176:179], v[184:187], v[120:123]
	v_mfma_i32_16x16x64_i8 v[120:123], v[180:183], v[188:191], v[120:123]
	v_mfma_i32_16x16x64_i8 v[84:87], v[168:171], v[192:195], v[84:87]
	v_mfma_i32_16x16x64_i8 v[84:87], v[172:175], v[196:199], v[84:87]
	v_mfma_i32_16x16x64_i8 v[116:119], v[176:179], v[192:195], v[116:119]
	v_mfma_i32_16x16x64_i8 v[116:119], v[180:183], v[196:199], v[116:119]
	v_mfma_i32_16x16x64_i8 v[80:83], v[168:171], v[200:203], v[80:83]
	v_mfma_i32_16x16x64_i8 v[80:83], v[172:175], v[204:207], v[80:83]
	v_mfma_i32_16x16x64_i8 v[112:115], v[176:179], v[200:203], v[112:115]
	v_mfma_i32_16x16x64_i8 v[112:115], v[180:183], v[204:207], v[112:115]
	s_setprio 2
	s_barrier
	v_mfma_i32_16x16x64_i8 v[76:79], v[168:171], v[208:211], v[76:79]
	v_mfma_i32_16x16x64_i8 v[76:79], v[172:175], v[212:215], v[76:79]
	v_mfma_i32_16x16x64_i8 v[108:111], v[176:179], v[208:211], v[108:111]
	v_mfma_i32_16x16x64_i8 v[108:111], v[180:183], v[212:215], v[108:111]
	s_setprio 0
	s_add_i32 s36, s36, s63
	s_mov_b32 m0, s36
	ds_read_b128 v[184:187], v161 offset:49152
	ds_read_b128 v[188:191], v161 offset:50176
	ds_read_b128 v[192:195], v161 offset:51200
	ds_read_b128 v[196:199], v161 offset:52224
	ds_read_b128 v[200:203], v161 offset:53248
	ds_read_b128 v[204:207], v161 offset:54272
	ds_read_b128 v[208:211], v161 offset:55296
	ds_read_b128 v[212:215], v161 offset:56320
	s_add_u32 s98, vcc_lo, s46
	s_addc_u32 s99, vcc_hi, s47
	global_load_lds_dwordx4 v138, s[98:99]
	s_add_i32 m0, s36, 0x2000
	s_add_i32 s36, s37, s63
	s_add_u32 s98, vcc_lo, s48
	s_addc_u32 s99, vcc_hi, s49
	global_load_lds_dwordx4 v138, s[98:99]
	s_mov_b32 m0, s36
	s_add_u32 s98, vcc_lo, s54
	s_addc_u32 s99, vcc_hi, s55
	global_load_lds_dwordx4 v138, s[98:99]
	s_add_i32 m0, s36, 0x2000
	s_nop 0
	s_add_u32 s98, vcc_lo, s56
	s_addc_u32 s99, vcc_hi, s57
	global_load_lds_dwordx4 v138, s[98:99]
	s_mov_b32 m0, s95
	s_nop 0
	s_add_u32 s98, s80, s46
	s_addc_u32 s99, s81, s47
	global_load_lds_dwordx4 v136, s[98:99]
	s_mov_b32 m0, s82
	s_nop 0
	s_add_u32 s98, s80, s48
	s_addc_u32 s99, s81, s49
	global_load_lds_dwordx4 v136, s[98:99]
	s_waitcnt vmcnt(8)
	s_waitcnt lgkmcnt(0)
	s_barrier
	s_setprio 1
	s_waitcnt lgkmcnt(0)
	v_mfma_i32_16x16x64_i8 v[20:23], v[128:131], v[184:187], v[20:23]
	v_mfma_i32_16x16x64_i8 v[20:23], v[132:135], v[188:191], v[20:23]
	v_mfma_i32_16x16x64_i8 v[40:43], v[146:149], v[184:187], v[40:43]
	v_mfma_i32_16x16x64_i8 v[40:43], v[164:167], v[188:191], v[40:43]
	v_mfma_i32_16x16x64_i8 v[16:19], v[128:131], v[192:195], v[16:19]
	v_mfma_i32_16x16x64_i8 v[16:19], v[132:135], v[196:199], v[16:19]
	v_mfma_i32_16x16x64_i8 v[36:39], v[146:149], v[192:195], v[36:39]
	v_mfma_i32_16x16x64_i8 v[36:39], v[164:167], v[196:199], v[36:39]
	v_mfma_i32_16x16x64_i8 v[24:27], v[128:131], v[200:203], v[24:27]
	v_mfma_i32_16x16x64_i8 v[24:27], v[132:135], v[204:207], v[24:27]
	v_mfma_i32_16x16x64_i8 v[32:35], v[146:149], v[200:203], v[32:35]
	v_mfma_i32_16x16x64_i8 v[32:35], v[164:167], v[204:207], v[32:35]
	v_mfma_i32_16x16x64_i8 v[28:31], v[128:131], v[208:211], v[28:31]
	v_mfma_i32_16x16x64_i8 v[28:31], v[132:135], v[212:215], v[28:31]
	v_mfma_i32_16x16x64_i8 v[60:63], v[146:149], v[208:211], v[60:63]
	v_mfma_i32_16x16x64_i8 v[60:63], v[164:167], v[212:215], v[60:63]
	s_setprio 0
	s_setprio 1
	v_mfma_i32_16x16x64_i8 v[72:75], v[168:171], v[184:187], v[72:75]
	v_mfma_i32_16x16x64_i8 v[72:75], v[172:175], v[188:191], v[72:75]
	v_mfma_i32_16x16x64_i8 v[104:107], v[176:179], v[184:187], v[104:107]
	v_mfma_i32_16x16x64_i8 v[104:107], v[180:183], v[188:191], v[104:107]
	v_mfma_i32_16x16x64_i8 v[68:71], v[168:171], v[192:195], v[68:71]
	v_mfma_i32_16x16x64_i8 v[68:71], v[172:175], v[196:199], v[68:71]
	v_mfma_i32_16x16x64_i8 v[100:103], v[176:179], v[192:195], v[100:103]
	v_mfma_i32_16x16x64_i8 v[100:103], v[180:183], v[196:199], v[100:103]
	v_mfma_i32_16x16x64_i8 v[64:67], v[168:171], v[200:203], v[64:67]
	v_mfma_i32_16x16x64_i8 v[64:67], v[172:175], v[204:207], v[64:67]
	v_mfma_i32_16x16x64_i8 v[96:99], v[176:179], v[200:203], v[96:99]
	v_mfma_i32_16x16x64_i8 v[96:99], v[180:183], v[204:207], v[96:99]
	s_setprio 2
	s_barrier
	v_mfma_i32_16x16x64_i8 v[92:95], v[168:171], v[208:211], v[92:95]
	v_mfma_i32_16x16x64_i8 v[92:95], v[172:175], v[212:215], v[92:95]
	v_mfma_i32_16x16x64_i8 v[124:127], v[176:179], v[208:211], v[124:127]
	v_mfma_i32_16x16x64_i8 v[124:127], v[180:183], v[212:215], v[124:127]
	s_setprio 0
	s_add_i32 s78, s78, 2
	s_add_u32 s24, s24, 0x100
	s_addc_u32 s45, s45, 0
	s_add_u32 s22, s22, 0x100
	s_addc_u32 s23, s23, 0
	s_cmp_gt_u32 s78, 29
	s_cbranch_scc0 .LBB0_225
	v_readlane_b32 s14, v250, 9
	v_readlane_b32 s15, v250, 10
	s_and_b64 vcc, exec, s[14:15]
	s_cbranch_vccz .LBB0_228
	s_barrier

.LBB0_298:
	ds_read_b128 v[128:131], v153
	ds_read_b128 v[132:135], v153 offset:1024
	ds_read_b128 v[146:149], v153 offset:2048
	ds_read_b128 v[158:161], v153 offset:3072
	ds_read_b128 v[162:165], v154
	ds_read_b128 v[166:169], v154 offset:1024
	ds_read_b128 v[170:173], v154 offset:2048
	ds_read_b128 v[174:177], v154 offset:3072
	s_add_u32 s36, s78, 0xfff00080
	s_addc_u32 s37, s79, -1
	s_cmp_eq_u32 s81, 60
	s_cselect_b32 s97, s5, s37
	s_cselect_b32 s96, s14, s36
	s_cselect_b32 vcc_hi, s20, s80
	s_cselect_b32 vcc_lo, s21, s22
	s_add_i32 m0, s33, 0xc000
	ds_read_b128 v[178:181], v155
	ds_read_b128 v[182:185], v155 offset:1024
	ds_read_b128 v[186:189], v155 offset:2048
	ds_read_b128 v[190:193], v155 offset:3072
	ds_read_b128 v[194:197], v155 offset:4096
	ds_read_b128 v[198:201], v155 offset:5120
	ds_read_b128 v[202:205], v155 offset:6144
	ds_read_b128 v[206:209], v155 offset:7168
	global_load_lds_dwordx4 v140, s[78:79]
	s_add_i32 m0, s33, 0xe000
	s_nop 0
	s_add_u32 s98, s78, s0
	s_addc_u32 s99, s79, s1
	global_load_lds_dwordx4 v140, s[98:99]
	s_waitcnt vmcnt(8)
	s_waitcnt lgkmcnt(0)
	s_barrier
	s_setprio 1
	s_waitcnt lgkmcnt(0)
	v_mfma_f32_16x16x32_bf16 v[124:127], v[128:131], v[178:181], v[124:127]
	v_mfma_f32_16x16x32_bf16 v[124:127], v[132:135], v[182:185], v[124:127]
	v_mfma_f32_16x16x32_bf16 v[120:123], v[146:149], v[178:181], v[120:123]
	v_mfma_f32_16x16x32_bf16 v[120:123], v[158:161], v[182:185], v[120:123]
	v_mfma_f32_16x16x32_bf16 v[112:115], v[128:131], v[186:189], v[112:115]
	v_mfma_f32_16x16x32_bf16 v[112:115], v[132:135], v[190:193], v[112:115]
	v_mfma_f32_16x16x32_bf16 v[108:111], v[146:149], v[186:189], v[108:111]
	v_mfma_f32_16x16x32_bf16 v[108:111], v[158:161], v[190:193], v[108:111]
	v_mfma_f32_16x16x32_bf16 v[100:103], v[128:131], v[194:197], v[100:103]
	v_mfma_f32_16x16x32_bf16 v[100:103], v[132:135], v[198:201], v[100:103]
	v_mfma_f32_16x16x32_bf16 v[92:95], v[146:149], v[194:197], v[92:95]
	v_mfma_f32_16x16x32_bf16 v[92:95], v[158:161], v[198:201], v[92:95]
	v_mfma_f32_16x16x32_bf16 v[84:87], v[128:131], v[202:205], v[84:87]
	v_mfma_f32_16x16x32_bf16 v[84:87], v[132:135], v[206:209], v[84:87]
	v_mfma_f32_16x16x32_bf16 v[76:79], v[146:149], v[202:205], v[76:79]
	v_mfma_f32_16x16x32_bf16 v[76:79], v[158:161], v[206:209], v[76:79]
	s_setprio 0
	s_setprio 1
	v_mfma_f32_16x16x32_bf16 v[116:119], v[162:165], v[178:181], v[116:119]
	v_mfma_f32_16x16x32_bf16 v[116:119], v[166:169], v[182:185], v[116:119]
	v_mfma_f32_16x16x32_bf16 v[104:107], v[170:173], v[178:181], v[104:107]
	v_mfma_f32_16x16x32_bf16 v[104:107], v[174:177], v[182:185], v[104:107]
	v_mfma_f32_16x16x32_bf16 v[96:99], v[162:165], v[186:189], v[96:99]
	v_mfma_f32_16x16x32_bf16 v[96:99], v[166:169], v[190:193], v[96:99]
	v_mfma_f32_16x16x32_bf16 v[88:91], v[170:173], v[186:189], v[88:91]
	v_mfma_f32_16x16x32_bf16 v[88:91], v[174:177], v[190:193], v[88:91]
	v_mfma_f32_16x16x32_bf16 v[80:83], v[162:165], v[194:197], v[80:83]
	v_mfma_f32_16x16x32_bf16 v[80:83], v[166:169], v[198:201], v[80:83]
	v_mfma_f32_16x16x32_bf16 v[72:75], v[170:173], v[194:197], v[72:75]
	v_mfma_f32_16x16x32_bf16 v[72:75], v[174:177], v[198:201], v[72:75]
	s_setprio 2
	s_barrier
	v_mfma_f32_16x16x32_bf16 v[68:71], v[162:165], v[202:205], v[68:71]
	v_mfma_f32_16x16x32_bf16 v[68:71], v[166:169], v[206:209], v[68:71]
	v_mfma_f32_16x16x32_bf16 v[64:67], v[170:173], v[202:205], v[64:67]
	v_mfma_f32_16x16x32_bf16 v[64:67], v[174:177], v[206:209], v[64:67]
	s_setprio 0
	s_add_i32 s36, s82, s63
	s_mov_b32 m0, s36
	ds_read_b128 v[178:181], v155 offset:16384
	ds_read_b128 v[182:185], v155 offset:17408
	ds_read_b128 v[186:189], v155 offset:18432
	ds_read_b128 v[190:193], v155 offset:19456
	ds_read_b128 v[194:197], v155 offset:20480
	ds_read_b128 v[198:201], v155 offset:21504
	ds_read_b128 v[202:205], v155 offset:22528
	ds_read_b128 v[206:209], v155 offset:23552
	global_load_lds_dwordx4 v138, vcc
	s_add_i32 m0, s36, 0x2000
	s_add_i32 s36, s83, s63
	s_add_u32 s98, vcc_lo, s0
	s_addc_u32 s99, vcc_hi, s1
	global_load_lds_dwordx4 v138, s[98:99]
	s_mov_b32 m0, s36
	s_nop 0
	s_add_u32 s98, vcc_lo, s6
	s_addc_u32 s99, vcc_hi, s7
	global_load_lds_dwordx4 v138, s[98:99]
	s_add_i32 m0, s36, 0x2000
	s_nop 0
	s_add_u32 s98, vcc_lo, s8
	s_addc_u32 s99, vcc_hi, s9
	global_load_lds_dwordx4 v138, s[98:99]
	s_mov_b32 m0, s33
	s_nop 0
	global_load_lds_dwordx4 v136, s[96:97]
	s_mov_b32 m0, s55
	s_nop 0
	s_add_u32 s98, s96, s0
	s_addc_u32 s99, s97, s1
	global_load_lds_dwordx4 v136, s[98:99]
	s_waitcnt vmcnt(8)
	s_waitcnt lgkmcnt(0)
	s_barrier
	s_setprio 1
	s_waitcnt lgkmcnt(0)
	v_mfma_f32_16x16x32_bf16 v[60:63], v[128:131], v[178:181], v[60:63]
	v_mfma_f32_16x16x32_bf16 v[60:63], v[132:135], v[182:185], v[60:63]
	v_mfma_f32_16x16x32_bf16 v[56:59], v[146:149], v[178:181], v[56:59]
	v_mfma_f32_16x16x32_bf16 v[56:59], v[158:161], v[182:185], v[56:59]
	v_mfma_f32_16x16x32_bf16 v[52:55], v[128:131], v[186:189], v[52:55]
	v_mfma_f32_16x16x32_bf16 v[52:55], v[132:135], v[190:193], v[52:55]
	v_mfma_f32_16x16x32_bf16 v[44:47], v[146:149], v[186:189], v[44:47]
	v_mfma_f32_16x16x32_bf16 v[44:47], v[158:161], v[190:193], v[44:47]
	v_mfma_f32_16x16x32_bf16 v[36:39], v[128:131], v[194:197], v[36:39]
	v_mfma_f32_16x16x32_bf16 v[36:39], v[132:135], v[198:201], v[36:39]
	v_mfma_f32_16x16x32_bf16 v[28:31], v[146:149], v[194:197], v[28:31]
	v_mfma_f32_16x16x32_bf16 v[28:31], v[158:161], v[198:201], v[28:31]
	v_mfma_f32_16x16x32_bf16 v[20:23], v[128:131], v[202:205], v[20:23]
	v_mfma_f32_16x16x32_bf16 v[20:23], v[132:135], v[206:209], v[20:23]
	v_mfma_f32_16x16x32_bf16 v[12:15], v[146:149], v[202:205], v[12:15]
	v_mfma_f32_16x16x32_bf16 v[12:15], v[158:161], v[206:209], v[12:15]
	s_setprio 0
	s_setprio 1
	v_mfma_f32_16x16x32_bf16 v[48:51], v[162:165], v[178:181], v[48:51]
	v_mfma_f32_16x16x32_bf16 v[48:51], v[166:169], v[182:185], v[48:51]
	v_mfma_f32_16x16x32_bf16 v[40:43], v[170:173], v[178:181], v[40:43]
	v_mfma_f32_16x16x32_bf16 v[40:43], v[174:177], v[182:185], v[40:43]
	v_mfma_f32_16x16x32_bf16 v[32:35], v[162:165], v[186:189], v[32:35]
	v_mfma_f32_16x16x32_bf16 v[32:35], v[166:169], v[190:193], v[32:35]
	v_mfma_f32_16x16x32_bf16 v[24:27], v[170:173], v[186:189], v[24:27]
	v_mfma_f32_16x16x32_bf16 v[24:27], v[174:177], v[190:193], v[24:27]
	v_mfma_f32_16x16x32_bf16 v[16:19], v[162:165], v[194:197], v[16:19]
	v_mfma_f32_16x16x32_bf16 v[16:19], v[166:169], v[198:201], v[16:19]
	v_mfma_f32_16x16x32_bf16 v[8:11], v[170:173], v[194:197], v[8:11]
	v_mfma_f32_16x16x32_bf16 v[8:11], v[174:177], v[198:201], v[8:11]
	s_setprio 2
	s_barrier
	v_mfma_f32_16x16x32_bf16 v[4:7], v[162:165], v[202:205], v[4:7]
	v_mfma_f32_16x16x32_bf16 v[4:7], v[166:169], v[206:209], v[4:7]
	v_mfma_f32_16x16x32_bf16 v[0:3], v[170:173], v[202:205], v[0:3]
	v_mfma_f32_16x16x32_bf16 v[0:3], v[174:177], v[206:209], v[0:3]
	s_setprio 0
	s_add_i32 s36, 0, 0x18000
	v_add_u32_e32 v157, s36, v152
	s_add_i32 s37, 0, 0x1c000
	ds_read_b128 v[128:131], v157
	ds_read_b128 v[132:135], v157 offset:1024
	ds_read_b128 v[146:149], v157 offset:2048
	ds_read_b128 v[158:161], v157 offset:3072
	v_add_u32_e32 v157, s37, v152
	ds_read_b128 v[162:165], v157
	ds_read_b128 v[166:169], v157 offset:1024
	ds_read_b128 v[170:173], v157 offset:2048
	ds_read_b128 v[174:177], v157 offset:3072
	s_mov_b32 m0, s57
	ds_read_b128 v[178:181], v155 offset:32768
	ds_read_b128 v[182:185], v155 offset:33792
	ds_read_b128 v[186:189], v155 offset:34816
	ds_read_b128 v[190:193], v155 offset:35840
	ds_read_b128 v[194:197], v155 offset:36864
	ds_read_b128 v[198:201], v155 offset:37888
	ds_read_b128 v[202:205], v155 offset:38912
	ds_read_b128 v[206:209], v155 offset:39936
	s_add_u32 s98, s96, s6
	s_addc_u32 s99, s97, s7
	global_load_lds_dwordx4 v136, s[98:99]
	s_mov_b32 m0, s59
	s_nop 0
	s_add_u32 s98, s96, s8
	s_addc_u32 s99, s97, s9
	global_load_lds_dwordx4 v136, s[98:99]
	s_waitcnt vmcnt(8)
	s_waitcnt lgkmcnt(0)
	s_barrier
	s_setprio 1
	s_waitcnt lgkmcnt(0)
	v_mfma_f32_16x16x32_bf16 v[124:127], v[128:131], v[178:181], v[124:127]
	v_mfma_f32_16x16x32_bf16 v[124:127], v[132:135], v[182:185], v[124:127]
	v_mfma_f32_16x16x32_bf16 v[120:123], v[146:149], v[178:181], v[120:123]
	v_mfma_f32_16x16x32_bf16 v[120:123], v[158:161], v[182:185], v[120:123]
	v_mfma_f32_16x16x32_bf16 v[112:115], v[128:131], v[186:189], v[112:115]
	v_mfma_f32_16x16x32_bf16 v[112:115], v[132:135], v[190:193], v[112:115]
	v_mfma_f32_16x16x32_bf16 v[108:111], v[146:149], v[186:189], v[108:111]
	v_mfma_f32_16x16x32_bf16 v[108:111], v[158:161], v[190:193], v[108:111]
	v_mfma_f32_16x16x32_bf16 v[100:103], v[128:131], v[194:197], v[100:103]
	v_mfma_f32_16x16x32_bf16 v[100:103], v[132:135], v[198:201], v[100:103]
	v_mfma_f32_16x16x32_bf16 v[92:95], v[146:149], v[194:197], v[92:95]
	v_mfma_f32_16x16x32_bf16 v[92:95], v[158:161], v[198:201], v[92:95]
	v_mfma_f32_16x16x32_bf16 v[84:87], v[128:131], v[202:205], v[84:87]
	v_mfma_f32_16x16x32_bf16 v[84:87], v[132:135], v[206:209], v[84:87]
	v_mfma_f32_16x16x32_bf16 v[76:79], v[146:149], v[202:205], v[76:79]
	v_mfma_f32_16x16x32_bf16 v[76:79], v[158:161], v[206:209], v[76:79]
	s_setprio 0
	s_setprio 1
	v_mfma_f32_16x16x32_bf16 v[116:119], v[162:165], v[178:181], v[116:119]
	v_mfma_f32_16x16x32_bf16 v[116:119], v[166:169], v[182:185], v[116:119]
	v_mfma_f32_16x16x32_bf16 v[104:107], v[170:173], v[178:181], v[104:107]
	v_mfma_f32_16x16x32_bf16 v[104:107], v[174:177], v[182:185], v[104:107]
	v_mfma_f32_16x16x32_bf16 v[96:99], v[162:165], v[186:189], v[96:99]
	v_mfma_f32_16x16x32_bf16 v[96:99], v[166:169], v[190:193], v[96:99]
	v_mfma_f32_16x16x32_bf16 v[88:91], v[170:173], v[186:189], v[88:91]
	v_mfma_f32_16x16x32_bf16 v[88:91], v[174:177], v[190:193], v[88:91]
	v_mfma_f32_16x16x32_bf16 v[80:83], v[162:165], v[194:197], v[80:83]
	v_mfma_f32_16x16x32_bf16 v[80:83], v[166:169], v[198:201], v[80:83]
	v_mfma_f32_16x16x32_bf16 v[72:75], v[170:173], v[194:197], v[72:75]
	v_mfma_f32_16x16x32_bf16 v[72:75], v[174:177], v[198:201], v[72:75]
	s_setprio 2
	s_barrier
	v_mfma_f32_16x16x32_bf16 v[68:71], v[162:165], v[202:205], v[68:71]
	v_mfma_f32_16x16x32_bf16 v[68:71], v[166:169], v[206:209], v[68:71]
	v_mfma_f32_16x16x32_bf16 v[64:67], v[170:173], v[202:205], v[64:67]
	v_mfma_f32_16x16x32_bf16 v[64:67], v[174:177], v[206:209], v[64:67]
	s_setprio 0
	s_add_i32 s36, s36, s63
	s_mov_b32 m0, s36
	ds_read_b128 v[178:181], v155 offset:49152
	ds_read_b128 v[182:185], v155 offset:50176
	ds_read_b128 v[186:189], v155 offset:51200
	ds_read_b128 v[190:193], v155 offset:52224
	ds_read_b128 v[194:197], v155 offset:53248
	ds_read_b128 v[198:201], v155 offset:54272
	ds_read_b128 v[202:205], v155 offset:55296
	ds_read_b128 v[206:209], v155 offset:56320
	s_add_u32 s98, vcc_lo, s24
	s_addc_u32 s99, vcc_hi, s25
	global_load_lds_dwordx4 v138, s[98:99]
	s_add_i32 m0, s36, 0x2000
	s_add_i32 s36, s37, s63
	s_add_u32 s98, vcc_lo, s34
	s_addc_u32 s99, vcc_hi, s35
	global_load_lds_dwordx4 v138, s[98:99]
	s_mov_b32 m0, s36
	s_add_u32 s98, vcc_lo, s12
	s_addc_u32 s99, vcc_hi, s13
	global_load_lds_dwordx4 v138, s[98:99]
	s_add_i32 m0, s36, 0x2000
	s_nop 0
	s_add_u32 s98, vcc_lo, s18
	s_addc_u32 s99, vcc_hi, s19
	global_load_lds_dwordx4 v138, s[98:99]
	s_mov_b32 m0, s68
	s_nop 0
	s_add_u32 s98, s96, s24
	s_addc_u32 s99, s97, s25
	global_load_lds_dwordx4 v136, s[98:99]
	s_mov_b32 m0, s69
	s_nop 0
	s_add_u32 s98, s96, s34
	s_addc_u32 s99, s97, s35
	global_load_lds_dwordx4 v136, s[98:99]
	s_waitcnt vmcnt(8)
	s_waitcnt lgkmcnt(0)
	s_barrier
	s_setprio 1
	s_waitcnt lgkmcnt(0)
	v_mfma_f32_16x16x32_bf16 v[60:63], v[128:131], v[178:181], v[60:63]
	v_mfma_f32_16x16x32_bf16 v[60:63], v[132:135], v[182:185], v[60:63]
	v_mfma_f32_16x16x32_bf16 v[56:59], v[146:149], v[178:181], v[56:59]
	v_mfma_f32_16x16x32_bf16 v[56:59], v[158:161], v[182:185], v[56:59]
	v_mfma_f32_16x16x32_bf16 v[52:55], v[128:131], v[186:189], v[52:55]
	v_mfma_f32_16x16x32_bf16 v[52:55], v[132:135], v[190:193], v[52:55]
	v_mfma_f32_16x16x32_bf16 v[44:47], v[146:149], v[186:189], v[44:47]
	v_mfma_f32_16x16x32_bf16 v[44:47], v[158:161], v[190:193], v[44:47]
	v_mfma_f32_16x16x32_bf16 v[36:39], v[128:131], v[194:197], v[36:39]
	v_mfma_f32_16x16x32_bf16 v[36:39], v[132:135], v[198:201], v[36:39]
	v_mfma_f32_16x16x32_bf16 v[28:31], v[146:149], v[194:197], v[28:31]
	v_mfma_f32_16x16x32_bf16 v[28:31], v[158:161], v[198:201], v[28:31]
	v_mfma_f32_16x16x32_bf16 v[20:23], v[128:131], v[202:205], v[20:23]
	v_mfma_f32_16x16x32_bf16 v[20:23], v[132:135], v[206:209], v[20:23]
	v_mfma_f32_16x16x32_bf16 v[12:15], v[146:149], v[202:205], v[12:15]
	v_mfma_f32_16x16x32_bf16 v[12:15], v[158:161], v[206:209], v[12:15]
	s_setprio 0
	s_setprio 1
	v_mfma_f32_16x16x32_bf16 v[48:51], v[162:165], v[178:181], v[48:51]
	v_mfma_f32_16x16x32_bf16 v[48:51], v[166:169], v[182:185], v[48:51]
	v_mfma_f32_16x16x32_bf16 v[40:43], v[170:173], v[178:181], v[40:43]
	v_mfma_f32_16x16x32_bf16 v[40:43], v[174:177], v[182:185], v[40:43]
	v_mfma_f32_16x16x32_bf16 v[32:35], v[162:165], v[186:189], v[32:35]
	v_mfma_f32_16x16x32_bf16 v[32:35], v[166:169], v[190:193], v[32:35]
	v_mfma_f32_16x16x32_bf16 v[24:27], v[170:173], v[186:189], v[24:27]
	v_mfma_f32_16x16x32_bf16 v[24:27], v[174:177], v[190:193], v[24:27]
	v_mfma_f32_16x16x32_bf16 v[16:19], v[162:165], v[194:197], v[16:19]
	v_mfma_f32_16x16x32_bf16 v[16:19], v[166:169], v[198:201], v[16:19]
	v_mfma_f32_16x16x32_bf16 v[8:11], v[170:173], v[194:197], v[8:11]
	v_mfma_f32_16x16x32_bf16 v[8:11], v[174:177], v[198:201], v[8:11]
	s_setprio 2
	s_barrier
	v_mfma_f32_16x16x32_bf16 v[4:7], v[162:165], v[202:205], v[4:7]
	v_mfma_f32_16x16x32_bf16 v[4:7], v[166:169], v[206:209], v[4:7]
	v_mfma_f32_16x16x32_bf16 v[0:3], v[170:173], v[202:205], v[0:3]
	v_mfma_f32_16x16x32_bf16 v[0:3], v[174:177], v[206:209], v[0:3]
	s_setprio 0
	s_add_i32 s81, s81, 2
	s_add_u32 s22, s22, 0x100
	s_addc_u32 s80, s80, 0
	s_add_u32 s78, s78, 0x100
	s_addc_u32 s79, s79, 0
	s_cmp_gt_u32 s81, 61
	s_cbranch_scc0 .LBB0_298
	s_and_b64 vcc, exec, s[26:27]
	s_cbranch_vccz .LBB0_301
	s_barrier

.LBB0_627:
	ds_read_b128 v[128:131], v151
	ds_read_b128 v[142:145], v151 offset:1024
	ds_read_b128 v[146:149], v151 offset:2048
	ds_read_b128 v[154:157], v151 offset:3072
	ds_read_b128 v[158:161], v152
	ds_read_b128 v[162:165], v152 offset:1024
	ds_read_b128 v[166:169], v152 offset:2048
	ds_read_b128 v[170:173], v152 offset:3072
	s_add_u32 s50, s60, 0xfff00080
	s_addc_u32 s51, s61, -1
	s_cmp_eq_u32 s62, 60
	s_cselect_b32 s77, s5, s51
	s_cselect_b32 s76, s49, s50
	s_cselect_b32 s79, s47, s75
	s_cselect_b32 s78, s59, s74
	s_add_i32 m0, s20, 0xc000
	ds_read_b128 v[174:177], v153
	ds_read_b128 v[178:181], v153 offset:1024
	ds_read_b128 v[182:185], v153 offset:2048
	ds_read_b128 v[186:189], v153 offset:3072
	ds_read_b128 v[190:193], v153 offset:4096
	ds_read_b128 v[194:197], v153 offset:5120
	ds_read_b128 v[198:201], v153 offset:6144
	ds_read_b128 v[202:205], v153 offset:7168
	global_load_lds_dwordx4 v136, s[60:61]
	s_add_i32 m0, s20, 0xe000
	s_nop 0
	s_add_u32 s98, s60, s6
	s_addc_u32 s99, s61, s7
	global_load_lds_dwordx4 v136, s[98:99]
	s_waitcnt vmcnt(8)
	s_waitcnt lgkmcnt(0)
	s_barrier
	s_setprio 1
	s_waitcnt lgkmcnt(0)
	v_mfma_f32_16x16x32_bf16 v[124:127], v[128:131], v[174:177], v[124:127]
	v_mfma_f32_16x16x32_bf16 v[124:127], v[142:145], v[178:181], v[124:127]
	v_mfma_f32_16x16x32_bf16 v[120:123], v[146:149], v[174:177], v[120:123]
	v_mfma_f32_16x16x32_bf16 v[120:123], v[154:157], v[178:181], v[120:123]
	v_mfma_f32_16x16x32_bf16 v[116:119], v[128:131], v[182:185], v[116:119]
	v_mfma_f32_16x16x32_bf16 v[116:119], v[142:145], v[186:189], v[116:119]
	v_mfma_f32_16x16x32_bf16 v[112:115], v[146:149], v[182:185], v[112:115]
	v_mfma_f32_16x16x32_bf16 v[112:115], v[154:157], v[186:189], v[112:115]
	v_mfma_f32_16x16x32_bf16 v[108:111], v[128:131], v[190:193], v[108:111]
	v_mfma_f32_16x16x32_bf16 v[108:111], v[142:145], v[194:197], v[108:111]
	v_mfma_f32_16x16x32_bf16 v[104:107], v[146:149], v[190:193], v[104:107]
	v_mfma_f32_16x16x32_bf16 v[104:107], v[154:157], v[194:197], v[104:107]
	v_mfma_f32_16x16x32_bf16 v[100:103], v[128:131], v[198:201], v[100:103]
	v_mfma_f32_16x16x32_bf16 v[100:103], v[142:145], v[202:205], v[100:103]
	v_mfma_f32_16x16x32_bf16 v[96:99], v[146:149], v[198:201], v[96:99]
	v_mfma_f32_16x16x32_bf16 v[96:99], v[154:157], v[202:205], v[96:99]
	s_setprio 0
	s_setprio 1
	v_mfma_f32_16x16x32_bf16 v[92:95], v[158:161], v[174:177], v[92:95]
	v_mfma_f32_16x16x32_bf16 v[92:95], v[162:165], v[178:181], v[92:95]
	v_mfma_f32_16x16x32_bf16 v[88:91], v[166:169], v[174:177], v[88:91]
	v_mfma_f32_16x16x32_bf16 v[88:91], v[170:173], v[178:181], v[88:91]
	v_mfma_f32_16x16x32_bf16 v[84:87], v[158:161], v[182:185], v[84:87]
	v_mfma_f32_16x16x32_bf16 v[84:87], v[162:165], v[186:189], v[84:87]
	v_mfma_f32_16x16x32_bf16 v[80:83], v[166:169], v[182:185], v[80:83]
	v_mfma_f32_16x16x32_bf16 v[80:83], v[170:173], v[186:189], v[80:83]
	v_mfma_f32_16x16x32_bf16 v[76:79], v[158:161], v[190:193], v[76:79]
	v_mfma_f32_16x16x32_bf16 v[76:79], v[162:165], v[194:197], v[76:79]
	v_mfma_f32_16x16x32_bf16 v[72:75], v[166:169], v[190:193], v[72:75]
	v_mfma_f32_16x16x32_bf16 v[72:75], v[170:173], v[194:197], v[72:75]
	s_setprio 2
	s_barrier
	v_mfma_f32_16x16x32_bf16 v[68:71], v[158:161], v[198:201], v[68:71]
	v_mfma_f32_16x16x32_bf16 v[68:71], v[162:165], v[202:205], v[68:71]
	v_mfma_f32_16x16x32_bf16 v[64:67], v[166:169], v[198:201], v[64:67]
	v_mfma_f32_16x16x32_bf16 v[64:67], v[170:173], v[202:205], v[64:67]
	s_setprio 0
	s_add_i32 s50, s72, s14
	s_mov_b32 m0, s50
	ds_read_b128 v[174:177], v153 offset:16384
	ds_read_b128 v[178:181], v153 offset:17408
	ds_read_b128 v[182:185], v153 offset:18432
	ds_read_b128 v[186:189], v153 offset:19456
	ds_read_b128 v[190:193], v153 offset:20480
	ds_read_b128 v[194:197], v153 offset:21504
	ds_read_b128 v[198:201], v153 offset:22528
	ds_read_b128 v[202:205], v153 offset:23552
	global_load_lds_dwordx4 v134, s[78:79]
	s_add_i32 m0, s50, 0x2000
	s_add_i32 s50, s73, s14
	s_add_u32 s98, s78, s6
	s_addc_u32 s99, s79, s7
	global_load_lds_dwordx4 v134, s[98:99]
	s_mov_b32 m0, s50
	s_nop 0
	s_add_u32 s98, s78, s8
	s_addc_u32 s99, s79, s9
	global_load_lds_dwordx4 v134, s[98:99]
	s_add_i32 m0, s50, 0x2000
	s_nop 0
	s_add_u32 s98, s78, s10
	s_addc_u32 s99, s79, s11
	global_load_lds_dwordx4 v134, s[98:99]
	s_mov_b32 m0, s20
	s_nop 0
	global_load_lds_dwordx4 v132, s[76:77]
	s_mov_b32 m0, s21
	s_nop 0
	s_add_u32 s98, s76, s6
	s_addc_u32 s99, s77, s7
	global_load_lds_dwordx4 v132, s[98:99]
	s_waitcnt vmcnt(8)
	s_waitcnt lgkmcnt(0)
	s_barrier
	s_setprio 1
	s_waitcnt lgkmcnt(0)
	v_mfma_f32_16x16x32_bf16 v[60:63], v[128:131], v[174:177], v[60:63]
	v_mfma_f32_16x16x32_bf16 v[60:63], v[142:145], v[178:181], v[60:63]
	v_mfma_f32_16x16x32_bf16 v[56:59], v[146:149], v[174:177], v[56:59]
	v_mfma_f32_16x16x32_bf16 v[56:59], v[154:157], v[178:181], v[56:59]
	v_mfma_f32_16x16x32_bf16 v[52:55], v[128:131], v[182:185], v[52:55]
	v_mfma_f32_16x16x32_bf16 v[52:55], v[142:145], v[186:189], v[52:55]
	v_mfma_f32_16x16x32_bf16 v[48:51], v[146:149], v[182:185], v[48:51]
	v_mfma_f32_16x16x32_bf16 v[48:51], v[154:157], v[186:189], v[48:51]
	v_mfma_f32_16x16x32_bf16 v[44:47], v[128:131], v[190:193], v[44:47]
	v_mfma_f32_16x16x32_bf16 v[44:47], v[142:145], v[194:197], v[44:47]
	v_mfma_f32_16x16x32_bf16 v[40:43], v[146:149], v[190:193], v[40:43]
	v_mfma_f32_16x16x32_bf16 v[40:43], v[154:157], v[194:197], v[40:43]
	v_mfma_f32_16x16x32_bf16 v[36:39], v[128:131], v[198:201], v[36:39]
	v_mfma_f32_16x16x32_bf16 v[36:39], v[142:145], v[202:205], v[36:39]
	v_mfma_f32_16x16x32_bf16 v[32:35], v[146:149], v[198:201], v[32:35]
	v_mfma_f32_16x16x32_bf16 v[32:35], v[154:157], v[202:205], v[32:35]
	s_setprio 0
	s_setprio 1
	v_mfma_f32_16x16x32_bf16 v[28:31], v[158:161], v[174:177], v[28:31]
	v_mfma_f32_16x16x32_bf16 v[28:31], v[162:165], v[178:181], v[28:31]
	v_mfma_f32_16x16x32_bf16 v[24:27], v[166:169], v[174:177], v[24:27]
	v_mfma_f32_16x16x32_bf16 v[24:27], v[170:173], v[178:181], v[24:27]
	v_mfma_f32_16x16x32_bf16 v[20:23], v[158:161], v[182:185], v[20:23]
	v_mfma_f32_16x16x32_bf16 v[20:23], v[162:165], v[186:189], v[20:23]
	v_mfma_f32_16x16x32_bf16 v[16:19], v[166:169], v[182:185], v[16:19]
	v_mfma_f32_16x16x32_bf16 v[16:19], v[170:173], v[186:189], v[16:19]
	v_mfma_f32_16x16x32_bf16 v[12:15], v[158:161], v[190:193], v[12:15]
	v_mfma_f32_16x16x32_bf16 v[12:15], v[162:165], v[194:197], v[12:15]
	v_mfma_f32_16x16x32_bf16 v[8:11], v[166:169], v[190:193], v[8:11]
	v_mfma_f32_16x16x32_bf16 v[8:11], v[170:173], v[194:197], v[8:11]
	s_setprio 2
	s_barrier
	v_mfma_f32_16x16x32_bf16 v[4:7], v[158:161], v[198:201], v[4:7]
	v_mfma_f32_16x16x32_bf16 v[4:7], v[162:165], v[202:205], v[4:7]
	v_mfma_f32_16x16x32_bf16 v[0:3], v[166:169], v[198:201], v[0:3]
	v_mfma_f32_16x16x32_bf16 v[0:3], v[170:173], v[202:205], v[0:3]
	s_setprio 0
	s_add_i32 s50, 0, 0x18000
	s_add_i32 s51, 0, 0x1c000
	v_add_u32_e32 v154, s50, v150
	v_add_u32_e32 v170, s51, v150
	ds_read_b128 v[128:131], v154
	ds_read_b128 v[142:145], v154 offset:1024
	ds_read_b128 v[146:149], v154 offset:2048
	ds_read_b128 v[154:157], v154 offset:3072
	ds_read_b128 v[158:161], v170
	ds_read_b128 v[162:165], v170 offset:1024
	ds_read_b128 v[166:169], v170 offset:2048
	ds_read_b128 v[170:173], v170 offset:3072
	s_mov_b32 m0, s33
	ds_read_b128 v[174:177], v153 offset:32768
	ds_read_b128 v[178:181], v153 offset:33792
	ds_read_b128 v[182:185], v153 offset:34816
	ds_read_b128 v[186:189], v153 offset:35840
	ds_read_b128 v[190:193], v153 offset:36864
	ds_read_b128 v[194:197], v153 offset:37888
	ds_read_b128 v[198:201], v153 offset:38912
	ds_read_b128 v[202:205], v153 offset:39936
	s_add_u32 s98, s76, s8
	s_addc_u32 s99, s77, s9
	global_load_lds_dwordx4 v132, s[98:99]
	s_mov_b32 m0, s64
	s_nop 0
	s_add_u32 s98, s76, s10
	s_addc_u32 s99, s77, s11
	global_load_lds_dwordx4 v132, s[98:99]
	s_waitcnt vmcnt(8)
	s_waitcnt lgkmcnt(0)
	s_barrier
	s_setprio 1
	s_waitcnt lgkmcnt(0)
	v_mfma_f32_16x16x32_bf16 v[124:127], v[128:131], v[174:177], v[124:127]
	v_mfma_f32_16x16x32_bf16 v[124:127], v[142:145], v[178:181], v[124:127]
	v_mfma_f32_16x16x32_bf16 v[120:123], v[146:149], v[174:177], v[120:123]
	v_mfma_f32_16x16x32_bf16 v[120:123], v[154:157], v[178:181], v[120:123]
	v_mfma_f32_16x16x32_bf16 v[116:119], v[128:131], v[182:185], v[116:119]
	v_mfma_f32_16x16x32_bf16 v[116:119], v[142:145], v[186:189], v[116:119]
	v_mfma_f32_16x16x32_bf16 v[112:115], v[146:149], v[182:185], v[112:115]
	v_mfma_f32_16x16x32_bf16 v[112:115], v[154:157], v[186:189], v[112:115]
	v_mfma_f32_16x16x32_bf16 v[108:111], v[128:131], v[190:193], v[108:111]
	v_mfma_f32_16x16x32_bf16 v[108:111], v[142:145], v[194:197], v[108:111]
	v_mfma_f32_16x16x32_bf16 v[104:107], v[146:149], v[190:193], v[104:107]
	v_mfma_f32_16x16x32_bf16 v[104:107], v[154:157], v[194:197], v[104:107]
	v_mfma_f32_16x16x32_bf16 v[100:103], v[128:131], v[198:201], v[100:103]
	v_mfma_f32_16x16x32_bf16 v[100:103], v[142:145], v[202:205], v[100:103]
	v_mfma_f32_16x16x32_bf16 v[96:99], v[146:149], v[198:201], v[96:99]
	v_mfma_f32_16x16x32_bf16 v[96:99], v[154:157], v[202:205], v[96:99]
	s_setprio 0
	s_setprio 1
	v_mfma_f32_16x16x32_bf16 v[92:95], v[158:161], v[174:177], v[92:95]
	v_mfma_f32_16x16x32_bf16 v[92:95], v[162:165], v[178:181], v[92:95]
	v_mfma_f32_16x16x32_bf16 v[88:91], v[166:169], v[174:177], v[88:91]
	v_mfma_f32_16x16x32_bf16 v[88:91], v[170:173], v[178:181], v[88:91]
	v_mfma_f32_16x16x32_bf16 v[84:87], v[158:161], v[182:185], v[84:87]
	v_mfma_f32_16x16x32_bf16 v[84:87], v[162:165], v[186:189], v[84:87]
	v_mfma_f32_16x16x32_bf16 v[80:83], v[166:169], v[182:185], v[80:83]
	v_mfma_f32_16x16x32_bf16 v[80:83], v[170:173], v[186:189], v[80:83]
	v_mfma_f32_16x16x32_bf16 v[76:79], v[158:161], v[190:193], v[76:79]
	v_mfma_f32_16x16x32_bf16 v[76:79], v[162:165], v[194:197], v[76:79]
	v_mfma_f32_16x16x32_bf16 v[72:75], v[166:169], v[190:193], v[72:75]
	v_mfma_f32_16x16x32_bf16 v[72:75], v[170:173], v[194:197], v[72:75]
	s_setprio 2
	s_barrier
	v_mfma_f32_16x16x32_bf16 v[68:71], v[158:161], v[198:201], v[68:71]
	v_mfma_f32_16x16x32_bf16 v[68:71], v[162:165], v[202:205], v[68:71]
	v_mfma_f32_16x16x32_bf16 v[64:67], v[166:169], v[198:201], v[64:67]
	v_mfma_f32_16x16x32_bf16 v[64:67], v[170:173], v[202:205], v[64:67]
	s_setprio 0
	s_add_i32 s50, s50, s14
	s_mov_b32 m0, s50
	ds_read_b128 v[174:177], v153 offset:49152
	ds_read_b128 v[178:181], v153 offset:50176
	ds_read_b128 v[182:185], v153 offset:51200
	ds_read_b128 v[186:189], v153 offset:52224
	ds_read_b128 v[190:193], v153 offset:53248
	ds_read_b128 v[194:197], v153 offset:54272
	ds_read_b128 v[198:201], v153 offset:55296
	ds_read_b128 v[202:205], v153 offset:56320
	s_add_u32 s98, s78, s24
	s_addc_u32 s99, s79, s25
	global_load_lds_dwordx4 v134, s[98:99]
	s_add_i32 m0, s50, 0x2000
	s_add_i32 s50, s51, s14
	s_add_u32 s98, s78, s34
	s_addc_u32 s99, s79, s35
	global_load_lds_dwordx4 v134, s[98:99]
	s_mov_b32 m0, s50
	s_add_u32 s98, s78, s36
	s_addc_u32 s99, s79, s37
	global_load_lds_dwordx4 v134, s[98:99]
	s_add_i32 m0, s50, 0x2000
	s_nop 0
	s_add_u32 s98, s78, s38
	s_addc_u32 s99, s79, s39
	global_load_lds_dwordx4 v134, s[98:99]
	s_mov_b32 m0, s66
	s_nop 0
	s_add_u32 s98, s76, s24
	s_addc_u32 s99, s77, s25
	global_load_lds_dwordx4 v132, s[98:99]
	s_mov_b32 m0, s67
	s_nop 0
	s_add_u32 s98, s76, s34
	s_addc_u32 s99, s77, s35
	global_load_lds_dwordx4 v132, s[98:99]
	s_waitcnt vmcnt(8)
	s_waitcnt lgkmcnt(0)
	s_barrier
	s_setprio 1
	s_waitcnt lgkmcnt(0)
	v_mfma_f32_16x16x32_bf16 v[60:63], v[128:131], v[174:177], v[60:63]
	v_mfma_f32_16x16x32_bf16 v[60:63], v[142:145], v[178:181], v[60:63]
	v_mfma_f32_16x16x32_bf16 v[56:59], v[146:149], v[174:177], v[56:59]
	v_mfma_f32_16x16x32_bf16 v[56:59], v[154:157], v[178:181], v[56:59]
	v_mfma_f32_16x16x32_bf16 v[52:55], v[128:131], v[182:185], v[52:55]
	v_mfma_f32_16x16x32_bf16 v[52:55], v[142:145], v[186:189], v[52:55]
	v_mfma_f32_16x16x32_bf16 v[48:51], v[146:149], v[182:185], v[48:51]
	v_mfma_f32_16x16x32_bf16 v[48:51], v[154:157], v[186:189], v[48:51]
	v_mfma_f32_16x16x32_bf16 v[44:47], v[128:131], v[190:193], v[44:47]
	v_mfma_f32_16x16x32_bf16 v[44:47], v[142:145], v[194:197], v[44:47]
	v_mfma_f32_16x16x32_bf16 v[40:43], v[146:149], v[190:193], v[40:43]
	v_mfma_f32_16x16x32_bf16 v[40:43], v[154:157], v[194:197], v[40:43]
	v_mfma_f32_16x16x32_bf16 v[36:39], v[128:131], v[198:201], v[36:39]
	v_mfma_f32_16x16x32_bf16 v[36:39], v[142:145], v[202:205], v[36:39]
	v_mfma_f32_16x16x32_bf16 v[32:35], v[146:149], v[198:201], v[32:35]
	v_mfma_f32_16x16x32_bf16 v[32:35], v[154:157], v[202:205], v[32:35]
	s_setprio 0
	s_setprio 1
	v_mfma_f32_16x16x32_bf16 v[28:31], v[158:161], v[174:177], v[28:31]
	v_mfma_f32_16x16x32_bf16 v[28:31], v[162:165], v[178:181], v[28:31]
	v_mfma_f32_16x16x32_bf16 v[24:27], v[166:169], v[174:177], v[24:27]
	v_mfma_f32_16x16x32_bf16 v[24:27], v[170:173], v[178:181], v[24:27]
	v_mfma_f32_16x16x32_bf16 v[20:23], v[158:161], v[182:185], v[20:23]
	v_mfma_f32_16x16x32_bf16 v[20:23], v[162:165], v[186:189], v[20:23]
	v_mfma_f32_16x16x32_bf16 v[16:19], v[166:169], v[182:185], v[16:19]
	v_mfma_f32_16x16x32_bf16 v[16:19], v[170:173], v[186:189], v[16:19]
	v_mfma_f32_16x16x32_bf16 v[12:15], v[158:161], v[190:193], v[12:15]
	v_mfma_f32_16x16x32_bf16 v[12:15], v[162:165], v[194:197], v[12:15]
	v_mfma_f32_16x16x32_bf16 v[8:11], v[166:169], v[190:193], v[8:11]
	v_mfma_f32_16x16x32_bf16 v[8:11], v[170:173], v[194:197], v[8:11]
	s_setprio 2
	s_barrier
	v_mfma_f32_16x16x32_bf16 v[4:7], v[158:161], v[198:201], v[4:7]
	v_mfma_f32_16x16x32_bf16 v[4:7], v[162:165], v[202:205], v[4:7]
	v_mfma_f32_16x16x32_bf16 v[0:3], v[166:169], v[198:201], v[0:3]
	v_mfma_f32_16x16x32_bf16 v[0:3], v[170:173], v[202:205], v[0:3]
	s_setprio 0
	s_add_i32 s62, s62, 2
	s_add_u32 s74, s74, 0x100
	s_addc_u32 s75, s75, 0
	s_add_u32 s60, s60, 0x100
	s_addc_u32 s61, s61, 0
	s_cmp_gt_u32 s62, 61
	s_cbranch_scc0 .LBB0_627
	s_and_b64 vcc, exec, s[40:41]
	s_cbranch_vccz .LBB0_630
	s_barrier

.LBB0_800:
	ds_read_b128 v[128:131], v187
	ds_read_b128 v[132:135], v187 offset:1024
	ds_read_b128 v[136:139], v187 offset:2048
	ds_read_b128 v[140:143], v187 offset:3072
	ds_read_b128 v[144:147], v188
	ds_read_b128 v[148:151], v188 offset:1024
	ds_read_b128 v[152:155], v188 offset:2048
	ds_read_b128 v[156:159], v188 offset:3072
	s_add_u32 s9, s6, 0xfff80080
	s_addc_u32 s50, s7, -1
	s_cmp_eq_u32 s8, 28
	s_cselect_b32 vcc_hi, s5, s50
	s_cselect_b32 vcc_lo, s10, s9
	s_cselect_b32 s51, s11, s78
	s_cselect_b32 s50, s73, s75
	s_add_i32 m0, s65, 0xc000
	ds_read_b128 v[160:163], v189
	ds_read_b128 v[164:167], v189 offset:1024
	ds_read_b128 v[168:171], v189 offset:2048
	ds_read_b128 v[192:195], v189 offset:3072
	ds_read_b128 v[196:199], v189 offset:4096
	ds_read_b128 v[200:203], v189 offset:5120
	ds_read_b128 v[204:207], v189 offset:6144
	ds_read_b128 v[208:211], v189 offset:7168
	global_load_lds_dwordx4 v178, s[6:7]
	s_add_i32 m0, s65, 0xe000
	s_nop 0
	s_add_u32 s98, s6, s36
	s_addc_u32 s99, s7, s37
	global_load_lds_dwordx4 v178, s[98:99]
	s_waitcnt vmcnt(8)
	s_waitcnt lgkmcnt(0)
	s_barrier
	s_setprio 1
	s_waitcnt lgkmcnt(0)
	v_mfma_i32_16x16x64_i8 v[84:87], v[128:131], v[160:163], v[84:87]
	v_mfma_i32_16x16x64_i8 v[84:87], v[132:135], v[164:167], v[84:87]
	v_mfma_i32_16x16x64_i8 v[16:19], v[136:139], v[160:163], v[16:19]
	v_mfma_i32_16x16x64_i8 v[16:19], v[140:143], v[164:167], v[16:19]
	v_mfma_i32_16x16x64_i8 v[88:91], v[128:131], v[168:171], v[88:91]
	v_mfma_i32_16x16x64_i8 v[88:91], v[132:135], v[192:195], v[88:91]
	v_mfma_i32_16x16x64_i8 v[20:23], v[136:139], v[168:171], v[20:23]
	v_mfma_i32_16x16x64_i8 v[20:23], v[140:143], v[192:195], v[20:23]
	v_mfma_i32_16x16x64_i8 v[92:95], v[128:131], v[196:199], v[92:95]
	v_mfma_i32_16x16x64_i8 v[92:95], v[132:135], v[200:203], v[92:95]
	v_mfma_i32_16x16x64_i8 v[24:27], v[136:139], v[196:199], v[24:27]
	v_mfma_i32_16x16x64_i8 v[24:27], v[140:143], v[200:203], v[24:27]
	v_mfma_i32_16x16x64_i8 v[96:99], v[128:131], v[204:207], v[96:99]
	v_mfma_i32_16x16x64_i8 v[96:99], v[132:135], v[208:211], v[96:99]
	v_mfma_i32_16x16x64_i8 v[28:31], v[136:139], v[204:207], v[28:31]
	v_mfma_i32_16x16x64_i8 v[28:31], v[140:143], v[208:211], v[28:31]
	s_setprio 0
	s_setprio 1
	v_mfma_i32_16x16x64_i8 v[124:127], v[144:147], v[160:163], v[124:127]
	v_mfma_i32_16x16x64_i8 v[124:127], v[148:151], v[164:167], v[124:127]
	v_mfma_i32_16x16x64_i8 v[68:71], v[152:155], v[160:163], v[68:71]
	v_mfma_i32_16x16x64_i8 v[68:71], v[156:159], v[164:167], v[68:71]
	v_mfma_i32_16x16x64_i8 v[120:123], v[144:147], v[168:171], v[120:123]
	v_mfma_i32_16x16x64_i8 v[120:123], v[148:151], v[192:195], v[120:123]
	v_mfma_i32_16x16x64_i8 v[72:75], v[152:155], v[168:171], v[72:75]
	v_mfma_i32_16x16x64_i8 v[72:75], v[156:159], v[192:195], v[72:75]
	v_mfma_i32_16x16x64_i8 v[116:119], v[144:147], v[196:199], v[116:119]
	v_mfma_i32_16x16x64_i8 v[116:119], v[148:151], v[200:203], v[116:119]
	v_mfma_i32_16x16x64_i8 v[80:83], v[152:155], v[196:199], v[80:83]
	v_mfma_i32_16x16x64_i8 v[80:83], v[156:159], v[200:203], v[80:83]
	s_setprio 2
	s_barrier
	v_mfma_i32_16x16x64_i8 v[112:115], v[144:147], v[204:207], v[112:115]
	v_mfma_i32_16x16x64_i8 v[112:115], v[148:151], v[208:211], v[112:115]
	v_mfma_i32_16x16x64_i8 v[60:63], v[152:155], v[204:207], v[60:63]
	v_mfma_i32_16x16x64_i8 v[60:63], v[156:159], v[208:211], v[60:63]
	s_setprio 0
	s_add_i32 s9, s80, s33
	s_mov_b64 s[100:101], s[50:51]
	s_mov_b32 m0, s9
	ds_read_b128 v[160:163], v189 offset:16384
	ds_read_b128 v[164:167], v189 offset:17408
	ds_read_b128 v[168:171], v189 offset:18432
	ds_read_b128 v[192:195], v189 offset:19456
	ds_read_b128 v[196:199], v189 offset:20480
	ds_read_b128 v[200:203], v189 offset:21504
	ds_read_b128 v[204:207], v189 offset:22528
	ds_read_b128 v[208:211], v189 offset:23552
	global_load_lds_dwordx4 v174, s[50:51]
	s_add_i32 m0, s9, 0x2000
	s_add_i32 s9, s81, s33
	s_add_u32 s98, s50, s36
	s_addc_u32 s99, s51, s37
	global_load_lds_dwordx4 v174, s[98:99]
	s_mov_b32 m0, s9
	s_nop 0
	s_add_u32 s98, s50, s38
	s_addc_u32 s99, s51, s39
	global_load_lds_dwordx4 v174, s[98:99]
	s_add_i32 m0, s9, 0x2000
	s_nop 0
	s_add_u32 s98, s50, s40
	s_addc_u32 s99, s51, s41
	global_load_lds_dwordx4 v174, s[98:99]
	s_mov_b32 m0, s65
	s_nop 0
	global_load_lds_dwordx4 v172, vcc
	s_mov_b32 m0, s67
	s_nop 0
	s_add_u32 s98, vcc_lo, s36
	s_addc_u32 s99, vcc_hi, s37
	global_load_lds_dwordx4 v172, s[98:99]
	s_waitcnt vmcnt(8)
	s_waitcnt lgkmcnt(0)
	s_barrier
	s_setprio 1
	s_waitcnt lgkmcnt(0)
	v_mfma_i32_16x16x64_i8 v[48:51], v[128:131], v[160:163], v[48:51]
	v_mfma_i32_16x16x64_i8 v[48:51], v[132:135], v[164:167], v[48:51]
	v_mfma_i32_16x16x64_i8 v[0:3], v[136:139], v[160:163], v[0:3]
	v_mfma_i32_16x16x64_i8 v[0:3], v[140:143], v[164:167], v[0:3]
	v_mfma_i32_16x16x64_i8 v[52:55], v[128:131], v[168:171], v[52:55]
	v_mfma_i32_16x16x64_i8 v[52:55], v[132:135], v[192:195], v[52:55]
	v_mfma_i32_16x16x64_i8 v[4:7], v[136:139], v[168:171], v[4:7]
	v_mfma_i32_16x16x64_i8 v[4:7], v[140:143], v[192:195], v[4:7]
	v_mfma_i32_16x16x64_i8 v[56:59], v[128:131], v[196:199], v[56:59]
	v_mfma_i32_16x16x64_i8 v[56:59], v[132:135], v[200:203], v[56:59]
	v_mfma_i32_16x16x64_i8 v[8:11], v[136:139], v[196:199], v[8:11]
	v_mfma_i32_16x16x64_i8 v[8:11], v[140:143], v[200:203], v[8:11]
	v_mfma_i32_16x16x64_i8 v[64:67], v[128:131], v[204:207], v[64:67]
	v_mfma_i32_16x16x64_i8 v[64:67], v[132:135], v[208:211], v[64:67]
	v_mfma_i32_16x16x64_i8 v[12:15], v[136:139], v[204:207], v[12:15]
	v_mfma_i32_16x16x64_i8 v[12:15], v[140:143], v[208:211], v[12:15]
	s_setprio 0
	s_setprio 1
	v_mfma_i32_16x16x64_i8 v[108:111], v[144:147], v[160:163], v[108:111]
	v_mfma_i32_16x16x64_i8 v[108:111], v[148:151], v[164:167], v[108:111]
	v_mfma_i32_16x16x64_i8 v[44:47], v[152:155], v[160:163], v[44:47]
	v_mfma_i32_16x16x64_i8 v[44:47], v[156:159], v[164:167], v[44:47]
	v_mfma_i32_16x16x64_i8 v[104:107], v[144:147], v[168:171], v[104:107]
	v_mfma_i32_16x16x64_i8 v[104:107], v[148:151], v[192:195], v[104:107]
	v_mfma_i32_16x16x64_i8 v[40:43], v[152:155], v[168:171], v[40:43]
	v_mfma_i32_16x16x64_i8 v[40:43], v[156:159], v[192:195], v[40:43]
	v_mfma_i32_16x16x64_i8 v[100:103], v[144:147], v[196:199], v[100:103]
	v_mfma_i32_16x16x64_i8 v[100:103], v[148:151], v[200:203], v[100:103]
	v_mfma_i32_16x16x64_i8 v[32:35], v[152:155], v[196:199], v[32:35]
	v_mfma_i32_16x16x64_i8 v[32:35], v[156:159], v[200:203], v[32:35]
	s_setprio 2
	s_barrier
	v_mfma_i32_16x16x64_i8 v[76:79], v[144:147], v[204:207], v[76:79]
	v_mfma_i32_16x16x64_i8 v[76:79], v[148:151], v[208:211], v[76:79]
	v_mfma_i32_16x16x64_i8 v[36:39], v[152:155], v[204:207], v[36:39]
	v_mfma_i32_16x16x64_i8 v[36:39], v[156:159], v[208:211], v[36:39]
	s_setprio 0
	s_add_i32 s9, 0, 0x18000
	s_add_i32 s50, 0, 0x1c000
	v_add_u32_e32 v140, s9, v186
	v_add_u32_e32 v156, s50, v186
	ds_read_b128 v[128:131], v140
	ds_read_b128 v[132:135], v140 offset:1024
	ds_read_b128 v[136:139], v140 offset:2048
	ds_read_b128 v[140:143], v140 offset:3072
	ds_read_b128 v[144:147], v156
	ds_read_b128 v[148:151], v156 offset:1024
	ds_read_b128 v[152:155], v156 offset:2048
	ds_read_b128 v[156:159], v156 offset:3072
	s_mov_b32 m0, s71
	ds_read_b128 v[160:163], v189 offset:32768
	ds_read_b128 v[164:167], v189 offset:33792
	ds_read_b128 v[168:171], v189 offset:34816
	ds_read_b128 v[192:195], v189 offset:35840
	ds_read_b128 v[196:199], v189 offset:36864
	ds_read_b128 v[200:203], v189 offset:37888
	ds_read_b128 v[204:207], v189 offset:38912
	ds_read_b128 v[208:211], v189 offset:39936
	s_add_u32 s98, vcc_lo, s38
	s_addc_u32 s99, vcc_hi, s39
	global_load_lds_dwordx4 v172, s[98:99]
	s_mov_b32 m0, s82
	s_nop 0
	s_add_u32 s98, vcc_lo, s40
	s_addc_u32 s99, vcc_hi, s41
	global_load_lds_dwordx4 v172, s[98:99]
	s_waitcnt vmcnt(8)
	s_waitcnt lgkmcnt(0)
	s_barrier
	s_setprio 1
	s_waitcnt lgkmcnt(0)
	v_mfma_i32_16x16x64_i8 v[84:87], v[128:131], v[160:163], v[84:87]
	v_mfma_i32_16x16x64_i8 v[84:87], v[132:135], v[164:167], v[84:87]
	v_mfma_i32_16x16x64_i8 v[16:19], v[136:139], v[160:163], v[16:19]
	v_mfma_i32_16x16x64_i8 v[16:19], v[140:143], v[164:167], v[16:19]
	v_mfma_i32_16x16x64_i8 v[88:91], v[128:131], v[168:171], v[88:91]
	v_mfma_i32_16x16x64_i8 v[88:91], v[132:135], v[192:195], v[88:91]
	v_mfma_i32_16x16x64_i8 v[20:23], v[136:139], v[168:171], v[20:23]
	v_mfma_i32_16x16x64_i8 v[20:23], v[140:143], v[192:195], v[20:23]
	v_mfma_i32_16x16x64_i8 v[92:95], v[128:131], v[196:199], v[92:95]
	v_mfma_i32_16x16x64_i8 v[92:95], v[132:135], v[200:203], v[92:95]
	v_mfma_i32_16x16x64_i8 v[24:27], v[136:139], v[196:199], v[24:27]
	v_mfma_i32_16x16x64_i8 v[24:27], v[140:143], v[200:203], v[24:27]
	v_mfma_i32_16x16x64_i8 v[96:99], v[128:131], v[204:207], v[96:99]
	v_mfma_i32_16x16x64_i8 v[96:99], v[132:135], v[208:211], v[96:99]
	v_mfma_i32_16x16x64_i8 v[28:31], v[136:139], v[204:207], v[28:31]
	v_mfma_i32_16x16x64_i8 v[28:31], v[140:143], v[208:211], v[28:31]
	s_setprio 0
	s_setprio 1
	v_mfma_i32_16x16x64_i8 v[124:127], v[144:147], v[160:163], v[124:127]
	v_mfma_i32_16x16x64_i8 v[124:127], v[148:151], v[164:167], v[124:127]
	v_mfma_i32_16x16x64_i8 v[68:71], v[152:155], v[160:163], v[68:71]
	v_mfma_i32_16x16x64_i8 v[68:71], v[156:159], v[164:167], v[68:71]
	v_mfma_i32_16x16x64_i8 v[120:123], v[144:147], v[168:171], v[120:123]
	v_mfma_i32_16x16x64_i8 v[120:123], v[148:151], v[192:195], v[120:123]
	v_mfma_i32_16x16x64_i8 v[72:75], v[152:155], v[168:171], v[72:75]
	v_mfma_i32_16x16x64_i8 v[72:75], v[156:159], v[192:195], v[72:75]
	v_mfma_i32_16x16x64_i8 v[116:119], v[144:147], v[196:199], v[116:119]
	v_mfma_i32_16x16x64_i8 v[116:119], v[148:151], v[200:203], v[116:119]
	v_mfma_i32_16x16x64_i8 v[80:83], v[152:155], v[196:199], v[80:83]
	v_mfma_i32_16x16x64_i8 v[80:83], v[156:159], v[200:203], v[80:83]
	s_setprio 2
	s_barrier
	v_mfma_i32_16x16x64_i8 v[112:115], v[144:147], v[204:207], v[112:115]
	v_mfma_i32_16x16x64_i8 v[112:115], v[148:151], v[208:211], v[112:115]
	v_mfma_i32_16x16x64_i8 v[60:63], v[152:155], v[204:207], v[60:63]
	v_mfma_i32_16x16x64_i8 v[60:63], v[156:159], v[208:211], v[60:63]
	s_setprio 0
	s_add_i32 s9, s9, s33
	s_mov_b32 m0, s9
	ds_read_b128 v[160:163], v189 offset:49152
	ds_read_b128 v[164:167], v189 offset:50176
	ds_read_b128 v[168:171], v189 offset:51200
	ds_read_b128 v[192:195], v189 offset:52224
	ds_read_b128 v[196:199], v189 offset:53248
	ds_read_b128 v[200:203], v189 offset:54272
	ds_read_b128 v[204:207], v189 offset:55296
	ds_read_b128 v[208:211], v189 offset:56320
	s_add_u32 s98, s100, s44
	s_addc_u32 s99, s101, s45
	global_load_lds_dwordx4 v174, s[98:99]
	s_add_i32 m0, s9, 0x2000
	s_add_i32 s9, s50, s33
	s_add_u32 s98, s100, s46
	s_addc_u32 s99, s101, s47
	global_load_lds_dwordx4 v174, s[98:99]
	s_mov_b32 m0, s9
	s_add_u32 s98, s100, s48
	s_addc_u32 s99, s101, s49
	global_load_lds_dwordx4 v174, s[98:99]
	s_add_i32 m0, s9, 0x2000
	s_nop 0
	s_add_u32 s98, s100, s52
	s_addc_u32 s99, s101, s53
	global_load_lds_dwordx4 v174, s[98:99]
	s_mov_b32 m0, s90
	s_nop 0
	s_add_u32 s98, vcc_lo, s44
	s_addc_u32 s99, vcc_hi, s45
	global_load_lds_dwordx4 v172, s[98:99]
	s_mov_b32 m0, s91
	s_nop 0
	s_add_u32 s98, vcc_lo, s46
	s_addc_u32 s99, vcc_hi, s47
	global_load_lds_dwordx4 v172, s[98:99]
	s_waitcnt vmcnt(8)
	s_waitcnt lgkmcnt(0)
	s_barrier
	s_setprio 1
	s_waitcnt lgkmcnt(0)
	v_mfma_i32_16x16x64_i8 v[48:51], v[128:131], v[160:163], v[48:51]
	v_mfma_i32_16x16x64_i8 v[48:51], v[132:135], v[164:167], v[48:51]
	v_mfma_i32_16x16x64_i8 v[0:3], v[136:139], v[160:163], v[0:3]
	v_mfma_i32_16x16x64_i8 v[0:3], v[140:143], v[164:167], v[0:3]
	v_mfma_i32_16x16x64_i8 v[52:55], v[128:131], v[168:171], v[52:55]
	v_mfma_i32_16x16x64_i8 v[52:55], v[132:135], v[192:195], v[52:55]
	v_mfma_i32_16x16x64_i8 v[4:7], v[136:139], v[168:171], v[4:7]
	v_mfma_i32_16x16x64_i8 v[4:7], v[140:143], v[192:195], v[4:7]
	v_mfma_i32_16x16x64_i8 v[56:59], v[128:131], v[196:199], v[56:59]
	v_mfma_i32_16x16x64_i8 v[56:59], v[132:135], v[200:203], v[56:59]
	v_mfma_i32_16x16x64_i8 v[8:11], v[136:139], v[196:199], v[8:11]
	v_mfma_i32_16x16x64_i8 v[8:11], v[140:143], v[200:203], v[8:11]
	v_mfma_i32_16x16x64_i8 v[64:67], v[128:131], v[204:207], v[64:67]
	v_mfma_i32_16x16x64_i8 v[64:67], v[132:135], v[208:211], v[64:67]
	v_mfma_i32_16x16x64_i8 v[12:15], v[136:139], v[204:207], v[12:15]
	v_mfma_i32_16x16x64_i8 v[12:15], v[140:143], v[208:211], v[12:15]
	s_setprio 0
	s_setprio 1
	v_mfma_i32_16x16x64_i8 v[108:111], v[144:147], v[160:163], v[108:111]
	v_mfma_i32_16x16x64_i8 v[108:111], v[148:151], v[164:167], v[108:111]
	v_mfma_i32_16x16x64_i8 v[44:47], v[152:155], v[160:163], v[44:47]
	v_mfma_i32_16x16x64_i8 v[44:47], v[156:159], v[164:167], v[44:47]
	v_mfma_i32_16x16x64_i8 v[104:107], v[144:147], v[168:171], v[104:107]
	v_mfma_i32_16x16x64_i8 v[104:107], v[148:151], v[192:195], v[104:107]
	v_mfma_i32_16x16x64_i8 v[40:43], v[152:155], v[168:171], v[40:43]
	v_mfma_i32_16x16x64_i8 v[40:43], v[156:159], v[192:195], v[40:43]
	v_mfma_i32_16x16x64_i8 v[100:103], v[144:147], v[196:199], v[100:103]
	v_mfma_i32_16x16x64_i8 v[100:103], v[148:151], v[200:203], v[100:103]
	v_mfma_i32_16x16x64_i8 v[32:35], v[152:155], v[196:199], v[32:35]
	v_mfma_i32_16x16x64_i8 v[32:35], v[156:159], v[200:203], v[32:35]
	s_setprio 2
	s_barrier
	v_mfma_i32_16x16x64_i8 v[76:79], v[144:147], v[204:207], v[76:79]
	v_mfma_i32_16x16x64_i8 v[76:79], v[148:151], v[208:211], v[76:79]
	v_mfma_i32_16x16x64_i8 v[36:39], v[152:155], v[204:207], v[36:39]
	v_mfma_i32_16x16x64_i8 v[36:39], v[156:159], v[208:211], v[36:39]
	s_setprio 0
	s_add_i32 s8, s8, 2
	s_add_u32 s75, s75, 0x100
	s_addc_u32 s78, s78, 0
	s_add_u32 s6, s6, 0x100
	s_addc_u32 s7, s7, 0
	s_cmp_gt_u32 s8, 29
	s_cbranch_scc0 .LBB0_800
	s_and_b64 vcc, exec, s[54:55]
	s_cbranch_vccz .LBB0_803
	s_barrier

.LBB0_1034:
	ds_read_b128 v[138:141], v151
	ds_read_b128 v[142:145], v151 offset:1024
	ds_read_b128 v[146:149], v151 offset:2048
	ds_read_b128 v[154:157], v151 offset:3072
	ds_read_b128 v[158:161], v152
	ds_read_b128 v[162:165], v152 offset:1024
	ds_read_b128 v[166:169], v152 offset:2048
	ds_read_b128 v[170:173], v152 offset:3072
	s_add_u32 s47, s44, 0xffd50080
	s_addc_u32 s64, s45, -1
	s_cmpk_eq_i32 s46, 0xa8
	s_cselect_b32 s65, s5, s64
	s_cselect_b32 s64, s4, s47
	s_cselect_b32 s67, s43, s63
	s_cselect_b32 s66, s42, s62
	s_add_i32 m0, s25, 0xc000
	ds_read_b128 v[174:177], v153
	ds_read_b128 v[178:181], v153 offset:1024
	ds_read_b128 v[182:185], v153 offset:2048
	ds_read_b128 v[186:189], v153 offset:3072
	ds_read_b128 v[190:193], v153 offset:4096
	ds_read_b128 v[194:197], v153 offset:5120
	ds_read_b128 v[198:201], v153 offset:6144
	ds_read_b128 v[202:205], v153 offset:7168
	global_load_lds_dwordx4 v132, s[44:45]
	s_add_i32 m0, s25, 0xe000
	s_nop 0
	s_add_u32 s98, s44, s0
	s_addc_u32 s99, s45, s1
	global_load_lds_dwordx4 v132, s[98:99]
	s_waitcnt vmcnt(8)
	s_waitcnt lgkmcnt(0)
	s_barrier
	s_setprio 1
	s_waitcnt lgkmcnt(0)
	v_mfma_f32_16x16x32_bf16 v[124:127], v[138:141], v[174:177], v[124:127]
	v_mfma_f32_16x16x32_bf16 v[124:127], v[142:145], v[178:181], v[124:127]
	v_mfma_f32_16x16x32_bf16 v[120:123], v[146:149], v[174:177], v[120:123]
	v_mfma_f32_16x16x32_bf16 v[120:123], v[154:157], v[178:181], v[120:123]
	v_mfma_f32_16x16x32_bf16 v[116:119], v[138:141], v[182:185], v[116:119]
	v_mfma_f32_16x16x32_bf16 v[116:119], v[142:145], v[186:189], v[116:119]
	v_mfma_f32_16x16x32_bf16 v[112:115], v[146:149], v[182:185], v[112:115]
	v_mfma_f32_16x16x32_bf16 v[112:115], v[154:157], v[186:189], v[112:115]
	v_mfma_f32_16x16x32_bf16 v[108:111], v[138:141], v[190:193], v[108:111]
	v_mfma_f32_16x16x32_bf16 v[108:111], v[142:145], v[194:197], v[108:111]
	v_mfma_f32_16x16x32_bf16 v[104:107], v[146:149], v[190:193], v[104:107]
	v_mfma_f32_16x16x32_bf16 v[104:107], v[154:157], v[194:197], v[104:107]
	v_mfma_f32_16x16x32_bf16 v[100:103], v[138:141], v[198:201], v[100:103]
	v_mfma_f32_16x16x32_bf16 v[100:103], v[142:145], v[202:205], v[100:103]
	v_mfma_f32_16x16x32_bf16 v[96:99], v[146:149], v[198:201], v[96:99]
	v_mfma_f32_16x16x32_bf16 v[96:99], v[154:157], v[202:205], v[96:99]
	s_setprio 0
	s_setprio 1
	v_mfma_f32_16x16x32_bf16 v[92:95], v[158:161], v[174:177], v[92:95]
	v_mfma_f32_16x16x32_bf16 v[92:95], v[162:165], v[178:181], v[92:95]
	v_mfma_f32_16x16x32_bf16 v[88:91], v[166:169], v[174:177], v[88:91]
	v_mfma_f32_16x16x32_bf16 v[88:91], v[170:173], v[178:181], v[88:91]
	v_mfma_f32_16x16x32_bf16 v[84:87], v[158:161], v[182:185], v[84:87]
	v_mfma_f32_16x16x32_bf16 v[84:87], v[162:165], v[186:189], v[84:87]
	v_mfma_f32_16x16x32_bf16 v[80:83], v[166:169], v[182:185], v[80:83]
	v_mfma_f32_16x16x32_bf16 v[80:83], v[170:173], v[186:189], v[80:83]
	v_mfma_f32_16x16x32_bf16 v[76:79], v[158:161], v[190:193], v[76:79]
	v_mfma_f32_16x16x32_bf16 v[76:79], v[162:165], v[194:197], v[76:79]
	v_mfma_f32_16x16x32_bf16 v[72:75], v[166:169], v[190:193], v[72:75]
	v_mfma_f32_16x16x32_bf16 v[72:75], v[170:173], v[194:197], v[72:75]
	s_setprio 2
	s_barrier
	v_mfma_f32_16x16x32_bf16 v[68:71], v[158:161], v[198:201], v[68:71]
	v_mfma_f32_16x16x32_bf16 v[68:71], v[162:165], v[202:205], v[68:71]
	v_mfma_f32_16x16x32_bf16 v[64:67], v[166:169], v[198:201], v[64:67]
	v_mfma_f32_16x16x32_bf16 v[64:67], v[170:173], v[202:205], v[64:67]
	s_setprio 0
	s_add_i32 s47, s56, s24
	s_mov_b32 m0, s47
	ds_read_b128 v[174:177], v153 offset:16384
	ds_read_b128 v[178:181], v153 offset:17408
	ds_read_b128 v[182:185], v153 offset:18432
	ds_read_b128 v[186:189], v153 offset:19456
	ds_read_b128 v[190:193], v153 offset:20480
	ds_read_b128 v[194:197], v153 offset:21504
	ds_read_b128 v[198:201], v153 offset:22528
	ds_read_b128 v[202:205], v153 offset:23552
	global_load_lds_dwordx4 v130, s[66:67]
	s_add_i32 m0, s47, 0x2000
	s_add_i32 s47, s57, s24
	s_add_u32 s98, s66, s0
	s_addc_u32 s99, s67, s1
	global_load_lds_dwordx4 v130, s[98:99]
	s_mov_b32 m0, s47
	s_nop 0
	s_add_u32 s98, s66, s6
	s_addc_u32 s99, s67, s7
	global_load_lds_dwordx4 v130, s[98:99]
	s_add_i32 m0, s47, 0x2000
	s_nop 0
	s_add_u32 s98, s66, s8
	s_addc_u32 s99, s67, s9
	global_load_lds_dwordx4 v130, s[98:99]
	s_mov_b64 s[100:101], s[64:65]
	s_mov_b32 m0, s25
	s_nop 0
	global_load_lds_dwordx4 v128, s[64:65]
	s_mov_b32 m0, s33
	s_nop 0
	s_add_u32 s98, s64, s0
	s_addc_u32 s99, s65, s1
	global_load_lds_dwordx4 v128, s[98:99]
	s_waitcnt vmcnt(8)
	s_waitcnt lgkmcnt(0)
	s_barrier
	s_setprio 1
	s_waitcnt lgkmcnt(0)
	v_mfma_f32_16x16x32_bf16 v[60:63], v[138:141], v[174:177], v[60:63]
	v_mfma_f32_16x16x32_bf16 v[60:63], v[142:145], v[178:181], v[60:63]
	v_mfma_f32_16x16x32_bf16 v[56:59], v[146:149], v[174:177], v[56:59]
	v_mfma_f32_16x16x32_bf16 v[56:59], v[154:157], v[178:181], v[56:59]
	v_mfma_f32_16x16x32_bf16 v[52:55], v[138:141], v[182:185], v[52:55]
	v_mfma_f32_16x16x32_bf16 v[52:55], v[142:145], v[186:189], v[52:55]
	v_mfma_f32_16x16x32_bf16 v[48:51], v[146:149], v[182:185], v[48:51]
	v_mfma_f32_16x16x32_bf16 v[48:51], v[154:157], v[186:189], v[48:51]
	v_mfma_f32_16x16x32_bf16 v[44:47], v[138:141], v[190:193], v[44:47]
	v_mfma_f32_16x16x32_bf16 v[44:47], v[142:145], v[194:197], v[44:47]
	v_mfma_f32_16x16x32_bf16 v[40:43], v[146:149], v[190:193], v[40:43]
	v_mfma_f32_16x16x32_bf16 v[40:43], v[154:157], v[194:197], v[40:43]
	v_mfma_f32_16x16x32_bf16 v[36:39], v[138:141], v[198:201], v[36:39]
	v_mfma_f32_16x16x32_bf16 v[36:39], v[142:145], v[202:205], v[36:39]
	v_mfma_f32_16x16x32_bf16 v[32:35], v[146:149], v[198:201], v[32:35]
	v_mfma_f32_16x16x32_bf16 v[32:35], v[154:157], v[202:205], v[32:35]
	s_setprio 0
	s_setprio 1
	v_mfma_f32_16x16x32_bf16 v[28:31], v[158:161], v[174:177], v[28:31]
	v_mfma_f32_16x16x32_bf16 v[28:31], v[162:165], v[178:181], v[28:31]
	v_mfma_f32_16x16x32_bf16 v[24:27], v[166:169], v[174:177], v[24:27]
	v_mfma_f32_16x16x32_bf16 v[24:27], v[170:173], v[178:181], v[24:27]
	v_mfma_f32_16x16x32_bf16 v[20:23], v[158:161], v[182:185], v[20:23]
	v_mfma_f32_16x16x32_bf16 v[20:23], v[162:165], v[186:189], v[20:23]
	v_mfma_f32_16x16x32_bf16 v[16:19], v[166:169], v[182:185], v[16:19]
	v_mfma_f32_16x16x32_bf16 v[16:19], v[170:173], v[186:189], v[16:19]
	v_mfma_f32_16x16x32_bf16 v[12:15], v[158:161], v[190:193], v[12:15]
	v_mfma_f32_16x16x32_bf16 v[12:15], v[162:165], v[194:197], v[12:15]
	v_mfma_f32_16x16x32_bf16 v[8:11], v[166:169], v[190:193], v[8:11]
	v_mfma_f32_16x16x32_bf16 v[8:11], v[170:173], v[194:197], v[8:11]
	s_setprio 2
	s_barrier
	v_mfma_f32_16x16x32_bf16 v[4:7], v[158:161], v[198:201], v[4:7]
	v_mfma_f32_16x16x32_bf16 v[4:7], v[162:165], v[202:205], v[4:7]
	v_mfma_f32_16x16x32_bf16 v[0:3], v[166:169], v[198:201], v[0:3]
	v_mfma_f32_16x16x32_bf16 v[0:3], v[170:173], v[202:205], v[0:3]
	s_setprio 0
	s_add_i32 s47, 0, 0x18000
	s_add_i32 s64, 0, 0x1c000
	v_add_u32_e32 v154, s47, v150
	v_add_u32_e32 v170, s64, v150
	ds_read_b128 v[138:141], v154
	ds_read_b128 v[142:145], v154 offset:1024
	ds_read_b128 v[146:149], v154 offset:2048
	ds_read_b128 v[154:157], v154 offset:3072
	ds_read_b128 v[158:161], v170
	ds_read_b128 v[162:165], v170 offset:1024
	ds_read_b128 v[166:169], v170 offset:2048
	ds_read_b128 v[170:173], v170 offset:3072
	s_mov_b32 m0, s48
	ds_read_b128 v[174:177], v153 offset:32768
	ds_read_b128 v[178:181], v153 offset:33792
	ds_read_b128 v[182:185], v153 offset:34816
	ds_read_b128 v[186:189], v153 offset:35840
	ds_read_b128 v[190:193], v153 offset:36864
	ds_read_b128 v[194:197], v153 offset:37888
	ds_read_b128 v[198:201], v153 offset:38912
	ds_read_b128 v[202:205], v153 offset:39936
	s_add_u32 s98, s100, s6
	s_addc_u32 s99, s101, s7
	global_load_lds_dwordx4 v128, s[98:99]
	s_mov_b32 m0, s49
	s_nop 0
	s_add_u32 s98, s100, s8
	s_addc_u32 s99, s101, s9
	global_load_lds_dwordx4 v128, s[98:99]
	s_waitcnt vmcnt(8)
	s_waitcnt lgkmcnt(0)
	s_barrier
	s_setprio 1
	s_waitcnt lgkmcnt(0)
	v_mfma_f32_16x16x32_bf16 v[124:127], v[138:141], v[174:177], v[124:127]
	v_mfma_f32_16x16x32_bf16 v[124:127], v[142:145], v[178:181], v[124:127]
	v_mfma_f32_16x16x32_bf16 v[120:123], v[146:149], v[174:177], v[120:123]
	v_mfma_f32_16x16x32_bf16 v[120:123], v[154:157], v[178:181], v[120:123]
	v_mfma_f32_16x16x32_bf16 v[116:119], v[138:141], v[182:185], v[116:119]
	v_mfma_f32_16x16x32_bf16 v[116:119], v[142:145], v[186:189], v[116:119]
	v_mfma_f32_16x16x32_bf16 v[112:115], v[146:149], v[182:185], v[112:115]
	v_mfma_f32_16x16x32_bf16 v[112:115], v[154:157], v[186:189], v[112:115]
	v_mfma_f32_16x16x32_bf16 v[108:111], v[138:141], v[190:193], v[108:111]
	v_mfma_f32_16x16x32_bf16 v[108:111], v[142:145], v[194:197], v[108:111]
	v_mfma_f32_16x16x32_bf16 v[104:107], v[146:149], v[190:193], v[104:107]
	v_mfma_f32_16x16x32_bf16 v[104:107], v[154:157], v[194:197], v[104:107]
	v_mfma_f32_16x16x32_bf16 v[100:103], v[138:141], v[198:201], v[100:103]
	v_mfma_f32_16x16x32_bf16 v[100:103], v[142:145], v[202:205], v[100:103]
	v_mfma_f32_16x16x32_bf16 v[96:99], v[146:149], v[198:201], v[96:99]
	v_mfma_f32_16x16x32_bf16 v[96:99], v[154:157], v[202:205], v[96:99]
	s_setprio 0
	s_setprio 1
	v_mfma_f32_16x16x32_bf16 v[92:95], v[158:161], v[174:177], v[92:95]
	v_mfma_f32_16x16x32_bf16 v[92:95], v[162:165], v[178:181], v[92:95]
	v_mfma_f32_16x16x32_bf16 v[88:91], v[166:169], v[174:177], v[88:91]
	v_mfma_f32_16x16x32_bf16 v[88:91], v[170:173], v[178:181], v[88:91]
	v_mfma_f32_16x16x32_bf16 v[84:87], v[158:161], v[182:185], v[84:87]
	v_mfma_f32_16x16x32_bf16 v[84:87], v[162:165], v[186:189], v[84:87]
	v_mfma_f32_16x16x32_bf16 v[80:83], v[166:169], v[182:185], v[80:83]
	v_mfma_f32_16x16x32_bf16 v[80:83], v[170:173], v[186:189], v[80:83]
	v_mfma_f32_16x16x32_bf16 v[76:79], v[158:161], v[190:193], v[76:79]
	v_mfma_f32_16x16x32_bf16 v[76:79], v[162:165], v[194:197], v[76:79]
	v_mfma_f32_16x16x32_bf16 v[72:75], v[166:169], v[190:193], v[72:75]
	v_mfma_f32_16x16x32_bf16 v[72:75], v[170:173], v[194:197], v[72:75]
	s_setprio 2
	s_barrier
	v_mfma_f32_16x16x32_bf16 v[68:71], v[158:161], v[198:201], v[68:71]
	v_mfma_f32_16x16x32_bf16 v[68:71], v[162:165], v[202:205], v[68:71]
	v_mfma_f32_16x16x32_bf16 v[64:67], v[166:169], v[198:201], v[64:67]
	v_mfma_f32_16x16x32_bf16 v[64:67], v[170:173], v[202:205], v[64:67]
	s_setprio 0
	s_add_i32 s47, s47, s24
	s_mov_b32 m0, s47
	ds_read_b128 v[174:177], v153 offset:49152
	ds_read_b128 v[178:181], v153 offset:50176
	ds_read_b128 v[182:185], v153 offset:51200
	ds_read_b128 v[186:189], v153 offset:52224
	ds_read_b128 v[190:193], v153 offset:53248
	ds_read_b128 v[194:197], v153 offset:54272
	ds_read_b128 v[198:201], v153 offset:55296
	ds_read_b128 v[202:205], v153 offset:56320
	s_add_u32 s98, s66, s16
	s_addc_u32 s99, s67, s17
	global_load_lds_dwordx4 v130, s[98:99]
	s_add_i32 m0, s47, 0x2000
	s_add_i32 s47, s64, s24
	s_add_u32 s98, s66, s20
	s_addc_u32 s99, s67, s21
	global_load_lds_dwordx4 v130, s[98:99]
	s_mov_b32 m0, s47
	s_add_u32 s98, s66, s34
	s_addc_u32 s99, s67, s35
	global_load_lds_dwordx4 v130, s[98:99]
	s_add_i32 m0, s47, 0x2000
	s_nop 0
	s_add_u32 s98, s66, s36
	s_addc_u32 s99, s67, s37
	global_load_lds_dwordx4 v130, s[98:99]
	s_mov_b32 m0, s51
	s_nop 0
	s_add_u32 s98, s100, s16
	s_addc_u32 s99, s101, s17
	global_load_lds_dwordx4 v128, s[98:99]
	s_mov_b32 m0, s52
	s_nop 0
	s_add_u32 s98, s100, s20
	s_addc_u32 s99, s101, s21
	global_load_lds_dwordx4 v128, s[98:99]
	s_waitcnt vmcnt(8)
	s_waitcnt lgkmcnt(0)
	s_barrier
	s_setprio 1
	s_waitcnt lgkmcnt(0)
	v_mfma_f32_16x16x32_bf16 v[60:63], v[138:141], v[174:177], v[60:63]
	v_mfma_f32_16x16x32_bf16 v[60:63], v[142:145], v[178:181], v[60:63]
	v_mfma_f32_16x16x32_bf16 v[56:59], v[146:149], v[174:177], v[56:59]
	v_mfma_f32_16x16x32_bf16 v[56:59], v[154:157], v[178:181], v[56:59]
	v_mfma_f32_16x16x32_bf16 v[52:55], v[138:141], v[182:185], v[52:55]
	v_mfma_f32_16x16x32_bf16 v[52:55], v[142:145], v[186:189], v[52:55]
	v_mfma_f32_16x16x32_bf16 v[48:51], v[146:149], v[182:185], v[48:51]
	v_mfma_f32_16x16x32_bf16 v[48:51], v[154:157], v[186:189], v[48:51]
	v_mfma_f32_16x16x32_bf16 v[44:47], v[138:141], v[190:193], v[44:47]
	v_mfma_f32_16x16x32_bf16 v[44:47], v[142:145], v[194:197], v[44:47]
	v_mfma_f32_16x16x32_bf16 v[40:43], v[146:149], v[190:193], v[40:43]
	v_mfma_f32_16x16x32_bf16 v[40:43], v[154:157], v[194:197], v[40:43]
	v_mfma_f32_16x16x32_bf16 v[36:39], v[138:141], v[198:201], v[36:39]
	v_mfma_f32_16x16x32_bf16 v[36:39], v[142:145], v[202:205], v[36:39]
	v_mfma_f32_16x16x32_bf16 v[32:35], v[146:149], v[198:201], v[32:35]
	v_mfma_f32_16x16x32_bf16 v[32:35], v[154:157], v[202:205], v[32:35]
	s_setprio 0
	s_setprio 1
	v_mfma_f32_16x16x32_bf16 v[28:31], v[158:161], v[174:177], v[28:31]
	v_mfma_f32_16x16x32_bf16 v[28:31], v[162:165], v[178:181], v[28:31]
	v_mfma_f32_16x16x32_bf16 v[24:27], v[166:169], v[174:177], v[24:27]
	v_mfma_f32_16x16x32_bf16 v[24:27], v[170:173], v[178:181], v[24:27]
	v_mfma_f32_16x16x32_bf16 v[20:23], v[158:161], v[182:185], v[20:23]
	v_mfma_f32_16x16x32_bf16 v[20:23], v[162:165], v[186:189], v[20:23]
	v_mfma_f32_16x16x32_bf16 v[16:19], v[166:169], v[182:185], v[16:19]
	v_mfma_f32_16x16x32_bf16 v[16:19], v[170:173], v[186:189], v[16:19]
	v_mfma_f32_16x16x32_bf16 v[12:15], v[158:161], v[190:193], v[12:15]
	v_mfma_f32_16x16x32_bf16 v[12:15], v[162:165], v[194:197], v[12:15]
	v_mfma_f32_16x16x32_bf16 v[8:11], v[166:169], v[190:193], v[8:11]
	v_mfma_f32_16x16x32_bf16 v[8:11], v[170:173], v[194:197], v[8:11]
	s_setprio 2
	s_barrier
	v_mfma_f32_16x16x32_bf16 v[4:7], v[158:161], v[198:201], v[4:7]
	v_mfma_f32_16x16x32_bf16 v[4:7], v[162:165], v[202:205], v[4:7]
	v_mfma_f32_16x16x32_bf16 v[0:3], v[166:169], v[198:201], v[0:3]
	v_mfma_f32_16x16x32_bf16 v[0:3], v[170:173], v[202:205], v[0:3]
	s_setprio 0
	s_add_i32 s46, s46, 2
	s_add_u32 s62, s62, 0x100
	s_addc_u32 s63, s63, 0
	s_add_u32 s44, s44, 0x100
	s_addc_u32 s45, s45, 0
	s_cmpk_gt_u32 s46, 0xa9
	s_cbranch_scc0 .LBB0_1034
	s_and_b64 vcc, exec, s[38:39]
	s_cbranch_vccz .LBB0_1037
	s_barrier

.LBB0_1180:
	ds_read_b128 v[112:115], v181
	ds_read_b128 v[116:119], v181 offset:1024
	ds_read_b128 v[128:131], v181 offset:2048
	ds_read_b128 v[142:145], v181 offset:3072
	ds_read_b128 v[146:149], v202
	ds_read_b128 v[150:153], v202 offset:1024
	ds_read_b128 v[154:157], v202 offset:2048
	ds_read_b128 v[168:171], v202 offset:3072
	s_add_u32 s49, s46, 0xfff80080
	s_addc_u32 s70, s47, -1
	s_cmp_eq_u32 s48, 28
	s_cselect_b32 s71, s39, s70
	s_cselect_b32 s70, s66, s49
	s_cselect_b32 s73, s37, s69
	s_cselect_b32 s72, s67, s68
	s_add_i32 m0, s45, 0xc000
	ds_read_b128 v[172:175], v203
	ds_read_b128 v[182:185], v203 offset:1024
	ds_read_b128 v[186:189], v203 offset:2048
	ds_read_b128 v[190:193], v203 offset:3072
	ds_read_b128 v[194:197], v203 offset:4096
	ds_read_b128 v[198:201], v203 offset:5120
	ds_read_b128 v[206:209], v203 offset:6144
	ds_read_b128 v[210:213], v203 offset:7168
	global_load_lds_dwordx4 v162, s[46:47]
	s_add_i32 m0, s45, 0xe000
	s_nop 0
	s_add_u32 s98, s46, s2
	s_addc_u32 s99, s47, s3
	global_load_lds_dwordx4 v162, s[98:99]
	s_waitcnt vmcnt(8)
	s_waitcnt lgkmcnt(0)
	s_barrier
	s_setprio 1
	s_waitcnt lgkmcnt(0)
	v_mfma_i32_16x16x64_i8 v[138:141], v[112:115], v[172:175], v[138:141]
	v_mfma_i32_16x16x64_i8 v[132:135], v[128:131], v[172:175], v[134:137]
	v_mfma_i32_16x16x64_i8 v[124:127], v[112:115], v[186:189], v[124:127]
	v_mfma_i32_16x16x64_i8 v[120:123], v[128:131], v[186:189], v[120:123]
	v_mfma_i32_16x16x64_i8 v[108:111], v[112:115], v[194:197], v[108:111]
	v_mfma_i32_16x16x64_i8 v[104:107], v[128:131], v[194:197], v[104:107]
	v_mfma_i32_16x16x64_i8 v[100:103], v[112:115], v[206:209], v[100:103]
	v_mfma_i32_16x16x64_i8 v[96:99], v[128:131], v[206:209], v[96:99]
	v_mfma_i32_16x16x64_i8 v[138:141], v[116:119], v[182:185], v[138:141]
	v_mfma_i32_16x16x64_i8 v[132:135], v[142:145], v[182:185], v[132:135]
	v_mfma_i32_16x16x64_i8 v[124:127], v[116:119], v[190:193], v[124:127]
	v_mfma_i32_16x16x64_i8 v[120:123], v[142:145], v[190:193], v[120:123]
	v_mfma_i32_16x16x64_i8 v[108:111], v[116:119], v[198:201], v[108:111]
	v_mfma_i32_16x16x64_i8 v[104:107], v[142:145], v[198:201], v[104:107]
	v_mfma_i32_16x16x64_i8 v[100:103], v[116:119], v[210:213], v[100:103]
	v_mfma_i32_16x16x64_i8 v[96:99], v[142:145], v[210:213], v[96:99]
	s_setprio 0
	s_setprio 1
	v_mfma_i32_16x16x64_i8 v[60:63], v[146:149], v[172:175], v[60:63]
	v_mfma_i32_16x16x64_i8 v[60:63], v[150:153], v[182:185], v[60:63]
	v_mfma_i32_16x16x64_i8 v[56:59], v[154:157], v[172:175], v[56:59]
	v_mfma_i32_16x16x64_i8 v[56:59], v[168:171], v[182:185], v[56:59]
	v_mfma_i32_16x16x64_i8 v[52:55], v[146:149], v[186:189], v[52:55]
	v_mfma_i32_16x16x64_i8 v[52:55], v[150:153], v[190:193], v[52:55]
	v_mfma_i32_16x16x64_i8 v[48:51], v[154:157], v[186:189], v[48:51]
	v_mfma_i32_16x16x64_i8 v[48:51], v[168:171], v[190:193], v[48:51]
	v_mfma_i32_16x16x64_i8 v[44:47], v[146:149], v[194:197], v[44:47]
	v_mfma_i32_16x16x64_i8 v[44:47], v[150:153], v[198:201], v[44:47]
	v_mfma_i32_16x16x64_i8 v[40:43], v[154:157], v[194:197], v[40:43]
	v_mfma_i32_16x16x64_i8 v[40:43], v[168:171], v[198:201], v[40:43]
	s_setprio 2
	s_barrier
	v_mfma_i32_16x16x64_i8 v[36:39], v[146:149], v[206:209], v[36:39]
	v_mfma_i32_16x16x64_i8 v[36:39], v[150:153], v[210:213], v[36:39]
	v_mfma_i32_16x16x64_i8 v[32:35], v[154:157], v[206:209], v[32:35]
	v_mfma_i32_16x16x64_i8 v[32:35], v[168:171], v[210:213], v[32:35]
	s_setprio 0
	s_add_i32 s49, s61, s33
	s_mov_b32 m0, s49
	ds_read_b128 v[172:175], v203 offset:16384
	ds_read_b128 v[182:185], v203 offset:17408
	ds_read_b128 v[186:189], v203 offset:18432
	ds_read_b128 v[190:193], v203 offset:19456
	ds_read_b128 v[194:197], v203 offset:20480
	ds_read_b128 v[198:201], v203 offset:21504
	ds_read_b128 v[206:209], v203 offset:22528
	ds_read_b128 v[210:213], v203 offset:23552
	global_load_lds_dwordx4 v160, s[72:73]
	s_add_i32 m0, s49, 0x2000
	s_add_i32 s49, s62, s33
	s_add_u32 s98, s72, s2
	s_addc_u32 s99, s73, s3
	global_load_lds_dwordx4 v160, s[98:99]
	s_mov_b32 m0, s49
	s_mov_b64 s[100:101], s[70:71]
	s_add_u32 s98, s72, s6
	s_addc_u32 s99, s73, s7
	global_load_lds_dwordx4 v160, s[98:99]
	s_add_i32 m0, s49, 0x2000
	s_nop 0
	s_add_u32 s98, s72, s8
	s_addc_u32 s99, s73, s9
	global_load_lds_dwordx4 v160, s[98:99]
	s_mov_b32 m0, s45
	s_nop 0
	global_load_lds_dwordx4 v158, s[70:71]
	s_mov_b32 m0, s50
	s_nop 0
	s_add_u32 s98, s70, s2
	s_addc_u32 s99, s71, s3
	global_load_lds_dwordx4 v158, s[98:99]
	s_waitcnt vmcnt(8)
	s_waitcnt lgkmcnt(0)
	s_barrier
	s_setprio 1
	s_waitcnt lgkmcnt(0)
	v_mfma_i32_16x16x64_i8 v[92:95], v[112:115], v[172:175], v[92:95]
	v_mfma_i32_16x16x64_i8 v[92:95], v[116:119], v[182:185], v[92:95]
	v_mfma_i32_16x16x64_i8 v[88:91], v[128:131], v[172:175], v[88:91]
	v_mfma_i32_16x16x64_i8 v[88:91], v[142:145], v[182:185], v[88:91]
	v_mfma_i32_16x16x64_i8 v[84:87], v[112:115], v[186:189], v[84:87]
	v_mfma_i32_16x16x64_i8 v[84:87], v[116:119], v[190:193], v[84:87]
	v_mfma_i32_16x16x64_i8 v[80:83], v[128:131], v[186:189], v[80:83]
	v_mfma_i32_16x16x64_i8 v[80:83], v[142:145], v[190:193], v[80:83]
	v_mfma_i32_16x16x64_i8 v[76:79], v[112:115], v[194:197], v[76:79]
	v_mfma_i32_16x16x64_i8 v[76:79], v[116:119], v[198:201], v[76:79]
	v_mfma_i32_16x16x64_i8 v[72:75], v[128:131], v[194:197], v[72:75]
	v_mfma_i32_16x16x64_i8 v[72:75], v[142:145], v[198:201], v[72:75]
	v_mfma_i32_16x16x64_i8 v[68:71], v[112:115], v[206:209], v[68:71]
	v_mfma_i32_16x16x64_i8 v[68:71], v[116:119], v[210:213], v[68:71]
	v_mfma_i32_16x16x64_i8 v[64:67], v[128:131], v[206:209], v[64:67]
	v_mfma_i32_16x16x64_i8 v[64:67], v[142:145], v[210:213], v[64:67]
	s_setprio 0
	s_setprio 1
	v_mfma_i32_16x16x64_i8 v[28:31], v[146:149], v[172:175], v[28:31]
	v_mfma_i32_16x16x64_i8 v[28:31], v[150:153], v[182:185], v[28:31]
	v_mfma_i32_16x16x64_i8 v[24:27], v[154:157], v[172:175], v[24:27]
	v_mfma_i32_16x16x64_i8 v[24:27], v[168:171], v[182:185], v[24:27]
	v_mfma_i32_16x16x64_i8 v[20:23], v[146:149], v[186:189], v[20:23]
	v_mfma_i32_16x16x64_i8 v[20:23], v[150:153], v[190:193], v[20:23]
	v_mfma_i32_16x16x64_i8 v[16:19], v[154:157], v[186:189], v[16:19]
	v_mfma_i32_16x16x64_i8 v[16:19], v[168:171], v[190:193], v[16:19]
	v_mfma_i32_16x16x64_i8 v[12:15], v[146:149], v[194:197], v[12:15]
	v_mfma_i32_16x16x64_i8 v[12:15], v[150:153], v[198:201], v[12:15]
	v_mfma_i32_16x16x64_i8 v[8:11], v[154:157], v[194:197], v[8:11]
	v_mfma_i32_16x16x64_i8 v[8:11], v[168:171], v[198:201], v[8:11]
	s_setprio 2
	s_barrier
	v_mfma_i32_16x16x64_i8 v[4:7], v[146:149], v[206:209], v[4:7]
	v_mfma_i32_16x16x64_i8 v[4:7], v[150:153], v[210:213], v[4:7]
	v_mfma_i32_16x16x64_i8 v[0:3], v[154:157], v[206:209], v[0:3]
	v_mfma_i32_16x16x64_i8 v[0:3], v[168:171], v[210:213], v[0:3]
	s_setprio 0
	s_add_i32 s49, 0, 0x18000
	v_add_u32_e32 v136, s49, v179
	s_add_i32 s70, 0, 0x1c000
	ds_read_b128 v[112:115], v136
	ds_read_b128 v[116:119], v136 offset:1024
	ds_read_b128 v[128:131], v136 offset:2048
	ds_read_b128 v[142:145], v136 offset:3072
	v_add_u32_e32 v136, s70, v179
	ds_read_b128 v[146:149], v136
	ds_read_b128 v[150:153], v136 offset:1024
	ds_read_b128 v[154:157], v136 offset:2048
	ds_read_b128 v[168:171], v136 offset:3072
	s_mov_b32 m0, s51
	ds_read_b128 v[172:175], v203 offset:32768
	ds_read_b128 v[182:185], v203 offset:33792
	ds_read_b128 v[186:189], v203 offset:34816
	ds_read_b128 v[190:193], v203 offset:35840
	ds_read_b128 v[194:197], v203 offset:36864
	ds_read_b128 v[198:201], v203 offset:37888
	ds_read_b128 v[206:209], v203 offset:38912
	ds_read_b128 v[210:213], v203 offset:39936
	s_add_u32 s98, s100, s6
	s_addc_u32 s99, s101, s7
	global_load_lds_dwordx4 v158, s[98:99]
	s_mov_b32 m0, s52
	s_nop 0
	s_add_u32 s98, s100, s8
	s_addc_u32 s99, s101, s9
	global_load_lds_dwordx4 v158, s[98:99]
	s_waitcnt vmcnt(8)
	s_waitcnt lgkmcnt(0)
	s_barrier
	s_setprio 1
	s_waitcnt lgkmcnt(0)
	v_mfma_i32_16x16x64_i8 v[136:139], v[112:115], v[172:175], v[138:141]
	v_mfma_i32_16x16x64_i8 v[132:135], v[128:131], v[172:175], v[132:135]
	v_mfma_i32_16x16x64_i8 v[124:127], v[112:115], v[186:189], v[124:127]
	v_mfma_i32_16x16x64_i8 v[120:123], v[128:131], v[186:189], v[120:123]
	v_mfma_i32_16x16x64_i8 v[108:111], v[112:115], v[194:197], v[108:111]
	v_mfma_i32_16x16x64_i8 v[104:107], v[128:131], v[194:197], v[104:107]
	v_mfma_i32_16x16x64_i8 v[100:103], v[112:115], v[206:209], v[100:103]
	v_mfma_i32_16x16x64_i8 v[96:99], v[128:131], v[206:209], v[96:99]
	v_mfma_i32_16x16x64_i8 v[138:141], v[116:119], v[182:185], v[136:139]
	v_mfma_i32_16x16x64_i8 v[134:137], v[142:145], v[182:185], v[132:135]
	v_mfma_i32_16x16x64_i8 v[124:127], v[116:119], v[190:193], v[124:127]
	v_mfma_i32_16x16x64_i8 v[120:123], v[142:145], v[190:193], v[120:123]
	v_mfma_i32_16x16x64_i8 v[108:111], v[116:119], v[198:201], v[108:111]
	v_mfma_i32_16x16x64_i8 v[104:107], v[142:145], v[198:201], v[104:107]
	v_mfma_i32_16x16x64_i8 v[100:103], v[116:119], v[210:213], v[100:103]
	v_mfma_i32_16x16x64_i8 v[96:99], v[142:145], v[210:213], v[96:99]
	s_setprio 0
	s_setprio 1
	v_mfma_i32_16x16x64_i8 v[60:63], v[146:149], v[172:175], v[60:63]
	v_mfma_i32_16x16x64_i8 v[60:63], v[150:153], v[182:185], v[60:63]
	v_mfma_i32_16x16x64_i8 v[56:59], v[154:157], v[172:175], v[56:59]
	v_mfma_i32_16x16x64_i8 v[56:59], v[168:171], v[182:185], v[56:59]
	v_mfma_i32_16x16x64_i8 v[52:55], v[146:149], v[186:189], v[52:55]
	v_mfma_i32_16x16x64_i8 v[52:55], v[150:153], v[190:193], v[52:55]
	v_mfma_i32_16x16x64_i8 v[48:51], v[154:157], v[186:189], v[48:51]
	v_mfma_i32_16x16x64_i8 v[48:51], v[168:171], v[190:193], v[48:51]
	v_mfma_i32_16x16x64_i8 v[44:47], v[146:149], v[194:197], v[44:47]
	v_mfma_i32_16x16x64_i8 v[44:47], v[150:153], v[198:201], v[44:47]
	v_mfma_i32_16x16x64_i8 v[40:43], v[154:157], v[194:197], v[40:43]
	v_mfma_i32_16x16x64_i8 v[40:43], v[168:171], v[198:201], v[40:43]
	s_setprio 2
	s_barrier
	v_mfma_i32_16x16x64_i8 v[36:39], v[146:149], v[206:209], v[36:39]
	v_mfma_i32_16x16x64_i8 v[36:39], v[150:153], v[210:213], v[36:39]
	v_mfma_i32_16x16x64_i8 v[32:35], v[154:157], v[206:209], v[32:35]
	v_mfma_i32_16x16x64_i8 v[32:35], v[168:171], v[210:213], v[32:35]
	s_setprio 0
	s_add_i32 s49, s49, s33
	s_mov_b32 m0, s49
	ds_read_b128 v[172:175], v203 offset:49152
	ds_read_b128 v[182:185], v203 offset:50176
	ds_read_b128 v[186:189], v203 offset:51200
	ds_read_b128 v[190:193], v203 offset:52224
	ds_read_b128 v[194:197], v203 offset:53248
	ds_read_b128 v[198:201], v203 offset:54272
	ds_read_b128 v[206:209], v203 offset:55296
	ds_read_b128 v[210:213], v203 offset:56320
	s_add_u32 s98, s72, s16
	s_addc_u32 s99, s73, s17
	global_load_lds_dwordx4 v160, s[98:99]
	s_add_i32 m0, s49, 0x2000
	s_add_i32 s49, s70, s33
	s_add_u32 s98, s72, s18
	s_addc_u32 s99, s73, s19
	global_load_lds_dwordx4 v160, s[98:99]
	s_mov_b32 m0, s49
	s_nop 0
	s_add_u32 s98, s72, s20
	s_addc_u32 s99, s73, s21
	global_load_lds_dwordx4 v160, s[98:99]
	s_add_i32 m0, s49, 0x2000
	s_nop 0
	s_add_u32 s98, s72, s30
	s_addc_u32 s99, s73, s31
	global_load_lds_dwordx4 v160, s[98:99]
	s_mov_b32 m0, s54
	s_nop 0
	s_add_u32 s98, s100, s16
	s_addc_u32 s99, s101, s17
	global_load_lds_dwordx4 v158, s[98:99]
	s_mov_b32 m0, s55
	s_nop 0
	s_add_u32 s98, s100, s18
	s_addc_u32 s99, s101, s19
	global_load_lds_dwordx4 v158, s[98:99]
	s_waitcnt vmcnt(8)
	s_waitcnt lgkmcnt(0)
	s_barrier
	s_setprio 1
	s_waitcnt lgkmcnt(0)
	v_mfma_i32_16x16x64_i8 v[92:95], v[112:115], v[172:175], v[92:95]
	v_mfma_i32_16x16x64_i8 v[92:95], v[116:119], v[182:185], v[92:95]
	v_mfma_i32_16x16x64_i8 v[88:91], v[128:131], v[172:175], v[88:91]
	v_mfma_i32_16x16x64_i8 v[88:91], v[142:145], v[182:185], v[88:91]
	v_mfma_i32_16x16x64_i8 v[84:87], v[112:115], v[186:189], v[84:87]
	v_mfma_i32_16x16x64_i8 v[84:87], v[116:119], v[190:193], v[84:87]
	v_mfma_i32_16x16x64_i8 v[80:83], v[128:131], v[186:189], v[80:83]
	v_mfma_i32_16x16x64_i8 v[80:83], v[142:145], v[190:193], v[80:83]
	v_mfma_i32_16x16x64_i8 v[76:79], v[112:115], v[194:197], v[76:79]
	v_mfma_i32_16x16x64_i8 v[76:79], v[116:119], v[198:201], v[76:79]
	v_mfma_i32_16x16x64_i8 v[72:75], v[128:131], v[194:197], v[72:75]
	v_mfma_i32_16x16x64_i8 v[72:75], v[142:145], v[198:201], v[72:75]
	v_mfma_i32_16x16x64_i8 v[68:71], v[112:115], v[206:209], v[68:71]
	v_mfma_i32_16x16x64_i8 v[68:71], v[116:119], v[210:213], v[68:71]
	v_mfma_i32_16x16x64_i8 v[64:67], v[128:131], v[206:209], v[64:67]
	v_mfma_i32_16x16x64_i8 v[64:67], v[142:145], v[210:213], v[64:67]
	s_setprio 0
	s_setprio 1
	v_mfma_i32_16x16x64_i8 v[28:31], v[146:149], v[172:175], v[28:31]
	v_mfma_i32_16x16x64_i8 v[28:31], v[150:153], v[182:185], v[28:31]
	v_mfma_i32_16x16x64_i8 v[24:27], v[154:157], v[172:175], v[24:27]
	v_mfma_i32_16x16x64_i8 v[24:27], v[168:171], v[182:185], v[24:27]
	v_mfma_i32_16x16x64_i8 v[20:23], v[146:149], v[186:189], v[20:23]
	v_mfma_i32_16x16x64_i8 v[20:23], v[150:153], v[190:193], v[20:23]
	v_mfma_i32_16x16x64_i8 v[16:19], v[154:157], v[186:189], v[16:19]
	v_mfma_i32_16x16x64_i8 v[16:19], v[168:171], v[190:193], v[16:19]
	v_mfma_i32_16x16x64_i8 v[12:15], v[146:149], v[194:197], v[12:15]
	v_mfma_i32_16x16x64_i8 v[12:15], v[150:153], v[198:201], v[12:15]
	v_mfma_i32_16x16x64_i8 v[8:11], v[154:157], v[194:197], v[8:11]
	v_mfma_i32_16x16x64_i8 v[8:11], v[168:171], v[198:201], v[8:11]
	s_setprio 2
	s_barrier
	v_mfma_i32_16x16x64_i8 v[4:7], v[146:149], v[206:209], v[4:7]
	v_mfma_i32_16x16x64_i8 v[4:7], v[150:153], v[210:213], v[4:7]
	v_mfma_i32_16x16x64_i8 v[0:3], v[154:157], v[206:209], v[0:3]
	v_mfma_i32_16x16x64_i8 v[0:3], v[168:171], v[210:213], v[0:3]
	s_setprio 0
	s_add_i32 s48, s48, 2
	s_add_u32 s68, s68, 0x100
	s_addc_u32 s69, s69, 0
	s_add_u32 s46, s46, 0x100
	s_addc_u32 s47, s47, 0
	s_cmp_gt_u32 s48, 29
	s_cbranch_scc0 .LBB0_1180
	s_and_b64 vcc, exec, s[34:35]
	s_cbranch_vccz .LBB0_1183
	s_barrier
